# phase0 mod_partials: all 138 loads of the item issued up front (single round trip)
# baseline (speedup 1.0000x reference)
.LBB0_20:
	v_mov_b32_e32 v0, v18
	v_lshlrev_b64 v[12:13], 2, v[0:1]
	v_lshl_add_u64 v[14:15], s[48:49], 0, v[12:13]
	v_lshl_add_u64 v[12:13], s[46:47], 0, v[12:13]
	global_load_dword v156, v[14:15], off
	global_load_dword v161, v[14:15], off offset:256
	global_load_dword v157, v[12:13], off
	global_load_dword v162, v[12:13], off offset:256
	v_add_co_u32_e32 v14, vcc, 0x1000, v12
	s_nop 1
	v_addc_co_u32_e32 v15, vcc, 0, v13, vcc
	global_load_dword v158, v[14:15], off
	global_load_dword v163, v[14:15], off offset:256
	v_add_co_u32_e32 v14, vcc, 0x1000, v14
	s_nop 1
	v_addc_co_u32_e32 v15, vcc, 0, v15, vcc
	global_load_dword v159, v[14:15], off
	global_load_dword v164, v[14:15], off offset:256
	v_add_co_u32_e32 v14, vcc, 0x1000, v14
	s_nop 1
	v_addc_co_u32_e32 v15, vcc, 0, v15, vcc
	global_load_dword v160, v[14:15], off
	global_load_dword v165, v[14:15], off offset:256
	v_mov_b32_e32 v12, v6
	v_mov_b32_e32 v13, v7
	global_load_dword v28, v[12:13], off nt
	v_add_co_u32_e32 v12, vcc, 0x3000, v12
	s_nop 1
	v_addc_co_u32_e32 v13, vcc, 0, v13, vcc
	global_load_dword v29, v[12:13], off nt
	v_add_co_u32_e32 v12, vcc, 0x3000, v12
	s_nop 1
	v_addc_co_u32_e32 v13, vcc, 0, v13, vcc
	global_load_dword v30, v[12:13], off nt
	v_add_co_u32_e32 v12, vcc, 0x3000, v12
	s_nop 1
	v_addc_co_u32_e32 v13, vcc, 0, v13, vcc
	global_load_dword v31, v[12:13], off nt
	v_add_co_u32_e32 v12, vcc, 0x3000, v12
	s_nop 1
	v_addc_co_u32_e32 v13, vcc, 0, v13, vcc
	global_load_dword v32, v[12:13], off nt
	v_add_co_u32_e32 v12, vcc, 0x3000, v12
	s_nop 1
	v_addc_co_u32_e32 v13, vcc, 0, v13, vcc
	global_load_dword v33, v[12:13], off nt
	v_add_co_u32_e32 v12, vcc, 0x3000, v12
	s_nop 1
	v_addc_co_u32_e32 v13, vcc, 0, v13, vcc
	global_load_dword v34, v[12:13], off nt
	v_add_co_u32_e32 v12, vcc, 0x3000, v12
	s_nop 1
	v_addc_co_u32_e32 v13, vcc, 0, v13, vcc
	global_load_dword v35, v[12:13], off nt
	v_add_co_u32_e32 v12, vcc, 0x3000, v12
	s_nop 1
	v_addc_co_u32_e32 v13, vcc, 0, v13, vcc
	global_load_dword v36, v[12:13], off nt
	v_add_co_u32_e32 v12, vcc, 0x3000, v12
	s_nop 1
	v_addc_co_u32_e32 v13, vcc, 0, v13, vcc
	global_load_dword v37, v[12:13], off nt
	v_add_co_u32_e32 v12, vcc, 0x3000, v12
	s_nop 1
	v_addc_co_u32_e32 v13, vcc, 0, v13, vcc
	global_load_dword v38, v[12:13], off nt
	v_add_co_u32_e32 v12, vcc, 0x3000, v12
	s_nop 1
	v_addc_co_u32_e32 v13, vcc, 0, v13, vcc
	global_load_dword v39, v[12:13], off nt
	v_add_co_u32_e32 v12, vcc, 0x3000, v12
	s_nop 1
	v_addc_co_u32_e32 v13, vcc, 0, v13, vcc
	global_load_dword v40, v[12:13], off nt
	v_add_co_u32_e32 v12, vcc, 0x3000, v12
	s_nop 1
	v_addc_co_u32_e32 v13, vcc, 0, v13, vcc
	global_load_dword v41, v[12:13], off nt
	v_add_co_u32_e32 v12, vcc, 0x3000, v12
	s_nop 1
	v_addc_co_u32_e32 v13, vcc, 0, v13, vcc
	global_load_dword v42, v[12:13], off nt
	v_add_co_u32_e32 v12, vcc, 0x3000, v12
	s_nop 1
	v_addc_co_u32_e32 v13, vcc, 0, v13, vcc
	global_load_dword v43, v[12:13], off nt
	v_add_co_u32_e32 v12, vcc, 0x3000, v12
	s_nop 1
	v_addc_co_u32_e32 v13, vcc, 0, v13, vcc
	global_load_dword v44, v[12:13], off nt
	v_add_co_u32_e32 v12, vcc, 0x3000, v12
	s_nop 1
	v_addc_co_u32_e32 v13, vcc, 0, v13, vcc
	global_load_dword v45, v[12:13], off nt
	v_add_co_u32_e32 v12, vcc, 0x3000, v12
	s_nop 1
	v_addc_co_u32_e32 v13, vcc, 0, v13, vcc
	global_load_dword v46, v[12:13], off nt
	v_add_co_u32_e32 v12, vcc, 0x3000, v12
	s_nop 1
	v_addc_co_u32_e32 v13, vcc, 0, v13, vcc
	global_load_dword v47, v[12:13], off nt
	v_add_co_u32_e32 v12, vcc, 0x3000, v12
	s_nop 1
	v_addc_co_u32_e32 v13, vcc, 0, v13, vcc
	global_load_dword v48, v[12:13], off nt
	v_add_co_u32_e32 v12, vcc, 0x3000, v12
	s_nop 1
	v_addc_co_u32_e32 v13, vcc, 0, v13, vcc
	global_load_dword v49, v[12:13], off nt
	v_add_co_u32_e32 v12, vcc, 0x3000, v12
	s_nop 1
	v_addc_co_u32_e32 v13, vcc, 0, v13, vcc
	global_load_dword v50, v[12:13], off nt
	v_add_co_u32_e32 v12, vcc, 0x3000, v12
	s_nop 1
	v_addc_co_u32_e32 v13, vcc, 0, v13, vcc
	global_load_dword v51, v[12:13], off nt
	v_add_co_u32_e32 v12, vcc, 0x3000, v12
	s_nop 1
	v_addc_co_u32_e32 v13, vcc, 0, v13, vcc
	global_load_dword v52, v[12:13], off nt
	v_add_co_u32_e32 v12, vcc, 0x3000, v12
	s_nop 1
	v_addc_co_u32_e32 v13, vcc, 0, v13, vcc
	global_load_dword v53, v[12:13], off nt
	v_add_co_u32_e32 v12, vcc, 0x3000, v12
	s_nop 1
	v_addc_co_u32_e32 v13, vcc, 0, v13, vcc
	global_load_dword v54, v[12:13], off nt
	v_add_co_u32_e32 v12, vcc, 0x3000, v12
	s_nop 1
	v_addc_co_u32_e32 v13, vcc, 0, v13, vcc
	global_load_dword v55, v[12:13], off nt
	v_add_co_u32_e32 v12, vcc, 0x3000, v12
	s_nop 1
	v_addc_co_u32_e32 v13, vcc, 0, v13, vcc
	global_load_dword v56, v[12:13], off nt
	v_add_co_u32_e32 v12, vcc, 0x3000, v12
	s_nop 1
	v_addc_co_u32_e32 v13, vcc, 0, v13, vcc
	global_load_dword v57, v[12:13], off nt
	v_add_co_u32_e32 v12, vcc, 0x3000, v12
	s_nop 1
	v_addc_co_u32_e32 v13, vcc, 0, v13, vcc
	global_load_dword v58, v[12:13], off nt
	v_add_co_u32_e32 v12, vcc, 0x3000, v12
	s_nop 1
	v_addc_co_u32_e32 v13, vcc, 0, v13, vcc
	global_load_dword v59, v[12:13], off nt
	v_add_co_u32_e32 v12, vcc, 0x3000, v12
	s_nop 1
	v_addc_co_u32_e32 v13, vcc, 0, v13, vcc
	global_load_dword v60, v[12:13], off nt
	v_add_co_u32_e32 v12, vcc, 0x3000, v12
	s_nop 1
	v_addc_co_u32_e32 v13, vcc, 0, v13, vcc
	global_load_dword v61, v[12:13], off nt
	v_add_co_u32_e32 v12, vcc, 0x3000, v12
	s_nop 1
	v_addc_co_u32_e32 v13, vcc, 0, v13, vcc
	global_load_dword v62, v[12:13], off nt
	v_add_co_u32_e32 v12, vcc, 0x3000, v12
	s_nop 1
	v_addc_co_u32_e32 v13, vcc, 0, v13, vcc
	global_load_dword v63, v[12:13], off nt
	v_add_co_u32_e32 v12, vcc, 0x3000, v12
	s_nop 1
	v_addc_co_u32_e32 v13, vcc, 0, v13, vcc
	global_load_dword v64, v[12:13], off nt
	v_add_co_u32_e32 v12, vcc, 0x3000, v12
	s_nop 1
	v_addc_co_u32_e32 v13, vcc, 0, v13, vcc
	global_load_dword v65, v[12:13], off nt
	v_add_co_u32_e32 v12, vcc, 0x3000, v12
	s_nop 1
	v_addc_co_u32_e32 v13, vcc, 0, v13, vcc
	global_load_dword v66, v[12:13], off nt
	v_add_co_u32_e32 v12, vcc, 0x3000, v12
	s_nop 1
	v_addc_co_u32_e32 v13, vcc, 0, v13, vcc
	global_load_dword v67, v[12:13], off nt
	v_add_co_u32_e32 v12, vcc, 0x3000, v12
	s_nop 1
	v_addc_co_u32_e32 v13, vcc, 0, v13, vcc
	global_load_dword v68, v[12:13], off nt
	v_add_co_u32_e32 v12, vcc, 0x3000, v12
	s_nop 1
	v_addc_co_u32_e32 v13, vcc, 0, v13, vcc
	global_load_dword v69, v[12:13], off nt
	v_add_co_u32_e32 v12, vcc, 0x3000, v12
	s_nop 1
	v_addc_co_u32_e32 v13, vcc, 0, v13, vcc
	global_load_dword v70, v[12:13], off nt
	v_add_co_u32_e32 v12, vcc, 0x3000, v12
	s_nop 1
	v_addc_co_u32_e32 v13, vcc, 0, v13, vcc
	global_load_dword v71, v[12:13], off nt
	v_add_co_u32_e32 v12, vcc, 0x3000, v12
	s_nop 1
	v_addc_co_u32_e32 v13, vcc, 0, v13, vcc
	global_load_dword v72, v[12:13], off nt
	v_add_co_u32_e32 v12, vcc, 0x3000, v12
	s_nop 1
	v_addc_co_u32_e32 v13, vcc, 0, v13, vcc
	global_load_dword v73, v[12:13], off nt
	v_add_co_u32_e32 v12, vcc, 0x3000, v12
	s_nop 1
	v_addc_co_u32_e32 v13, vcc, 0, v13, vcc
	global_load_dword v74, v[12:13], off nt
	v_add_co_u32_e32 v12, vcc, 0x3000, v12
	s_nop 1
	v_addc_co_u32_e32 v13, vcc, 0, v13, vcc
	global_load_dword v75, v[12:13], off nt
	v_add_co_u32_e32 v12, vcc, 0x3000, v12
	s_nop 1
	v_addc_co_u32_e32 v13, vcc, 0, v13, vcc
	global_load_dword v76, v[12:13], off nt
	v_add_co_u32_e32 v12, vcc, 0x3000, v12
	s_nop 1
	v_addc_co_u32_e32 v13, vcc, 0, v13, vcc
	global_load_dword v77, v[12:13], off nt
	v_add_co_u32_e32 v12, vcc, 0x3000, v12
	s_nop 1
	v_addc_co_u32_e32 v13, vcc, 0, v13, vcc
	global_load_dword v78, v[12:13], off nt
	v_add_co_u32_e32 v12, vcc, 0x3000, v12
	s_nop 1
	v_addc_co_u32_e32 v13, vcc, 0, v13, vcc
	global_load_dword v79, v[12:13], off nt
	v_add_co_u32_e32 v12, vcc, 0x3000, v12
	s_nop 1
	v_addc_co_u32_e32 v13, vcc, 0, v13, vcc
	global_load_dword v80, v[12:13], off nt
	v_add_co_u32_e32 v12, vcc, 0x3000, v12
	s_nop 1
	v_addc_co_u32_e32 v13, vcc, 0, v13, vcc
	global_load_dword v81, v[12:13], off nt
	v_add_co_u32_e32 v12, vcc, 0x3000, v12
	s_nop 1
	v_addc_co_u32_e32 v13, vcc, 0, v13, vcc
	global_load_dword v82, v[12:13], off nt
	v_add_co_u32_e32 v12, vcc, 0x3000, v12
	s_nop 1
	v_addc_co_u32_e32 v13, vcc, 0, v13, vcc
	global_load_dword v83, v[12:13], off nt
	v_add_co_u32_e32 v12, vcc, 0x3000, v12
	s_nop 1
	v_addc_co_u32_e32 v13, vcc, 0, v13, vcc
	global_load_dword v84, v[12:13], off nt
	v_add_co_u32_e32 v12, vcc, 0x3000, v12
	s_nop 1
	v_addc_co_u32_e32 v13, vcc, 0, v13, vcc
	global_load_dword v85, v[12:13], off nt
	v_add_co_u32_e32 v12, vcc, 0x3000, v12
	s_nop 1
	v_addc_co_u32_e32 v13, vcc, 0, v13, vcc
	global_load_dword v86, v[12:13], off nt
	v_add_co_u32_e32 v12, vcc, 0x3000, v12
	s_nop 1
	v_addc_co_u32_e32 v13, vcc, 0, v13, vcc
	global_load_dword v87, v[12:13], off nt
	v_add_co_u32_e32 v12, vcc, 0x3000, v12
	s_nop 1
	v_addc_co_u32_e32 v13, vcc, 0, v13, vcc
	global_load_dword v88, v[12:13], off nt
	v_add_co_u32_e32 v12, vcc, 0x3000, v12
	s_nop 1
	v_addc_co_u32_e32 v13, vcc, 0, v13, vcc
	global_load_dword v89, v[12:13], off nt
	v_add_co_u32_e32 v12, vcc, 0x3000, v12
	s_nop 1
	v_addc_co_u32_e32 v13, vcc, 0, v13, vcc
	global_load_dword v90, v[12:13], off nt
	v_add_co_u32_e32 v12, vcc, 0x3000, v12
	s_nop 1
	v_addc_co_u32_e32 v13, vcc, 0, v13, vcc
	global_load_dword v91, v[12:13], off nt
	v_add_co_u32_e32 v12, vcc, 0x3000, v12
	s_nop 1
	v_addc_co_u32_e32 v13, vcc, 0, v13, vcc
	global_load_dword v92, v[12:13], off nt
	v_add_co_u32_e32 v12, vcc, 0x3000, v12
	s_nop 1
	v_addc_co_u32_e32 v13, vcc, 0, v13, vcc
	global_load_dword v93, v[12:13], off nt
	v_add_co_u32_e32 v12, vcc, 0x3000, v12
	s_nop 1
	v_addc_co_u32_e32 v13, vcc, 0, v13, vcc
	global_load_dword v94, v[12:13], off nt
	v_add_co_u32_e32 v12, vcc, 0x3000, v12
	s_nop 1
	v_addc_co_u32_e32 v13, vcc, 0, v13, vcc
	global_load_dword v95, v[12:13], off nt
	v_add_co_u32_e32 v12, vcc, 0x3000, v12
	s_nop 1
	v_addc_co_u32_e32 v13, vcc, 0, v13, vcc
	global_load_dword v96, v[12:13], off nt
	v_add_co_u32_e32 v12, vcc, 0x3000, v12
	s_nop 1
	v_addc_co_u32_e32 v13, vcc, 0, v13, vcc
	global_load_dword v97, v[12:13], off nt
	v_add_co_u32_e32 v12, vcc, 0x3000, v12
	s_nop 1
	v_addc_co_u32_e32 v13, vcc, 0, v13, vcc
	global_load_dword v98, v[12:13], off nt
	v_add_co_u32_e32 v12, vcc, 0x3000, v12
	s_nop 1
	v_addc_co_u32_e32 v13, vcc, 0, v13, vcc
	global_load_dword v99, v[12:13], off nt
	v_add_co_u32_e32 v12, vcc, 0x3000, v12
	s_nop 1
	v_addc_co_u32_e32 v13, vcc, 0, v13, vcc
	global_load_dword v100, v[12:13], off nt
	v_add_co_u32_e32 v12, vcc, 0x3000, v12
	s_nop 1
	v_addc_co_u32_e32 v13, vcc, 0, v13, vcc
	global_load_dword v101, v[12:13], off nt
	v_add_co_u32_e32 v12, vcc, 0x3000, v12
	s_nop 1
	v_addc_co_u32_e32 v13, vcc, 0, v13, vcc
	global_load_dword v102, v[12:13], off nt
	v_add_co_u32_e32 v12, vcc, 0x3000, v12
	s_nop 1
	v_addc_co_u32_e32 v13, vcc, 0, v13, vcc
	global_load_dword v103, v[12:13], off nt
	v_add_co_u32_e32 v12, vcc, 0x3000, v12
	s_nop 1
	v_addc_co_u32_e32 v13, vcc, 0, v13, vcc
	global_load_dword v104, v[12:13], off nt
	v_add_co_u32_e32 v12, vcc, 0x3000, v12
	s_nop 1
	v_addc_co_u32_e32 v13, vcc, 0, v13, vcc
	global_load_dword v105, v[12:13], off nt
	v_add_co_u32_e32 v12, vcc, 0x3000, v12
	s_nop 1
	v_addc_co_u32_e32 v13, vcc, 0, v13, vcc
	global_load_dword v106, v[12:13], off nt
	v_add_co_u32_e32 v12, vcc, 0x3000, v12
	s_nop 1
	v_addc_co_u32_e32 v13, vcc, 0, v13, vcc
	global_load_dword v107, v[12:13], off nt
	v_add_co_u32_e32 v12, vcc, 0x3000, v12
	s_nop 1
	v_addc_co_u32_e32 v13, vcc, 0, v13, vcc
	global_load_dword v108, v[12:13], off nt
	v_add_co_u32_e32 v12, vcc, 0x3000, v12
	s_nop 1
	v_addc_co_u32_e32 v13, vcc, 0, v13, vcc
	global_load_dword v109, v[12:13], off nt
	v_add_co_u32_e32 v12, vcc, 0x3000, v12
	s_nop 1
	v_addc_co_u32_e32 v13, vcc, 0, v13, vcc
	global_load_dword v110, v[12:13], off nt
	v_add_co_u32_e32 v12, vcc, 0x3000, v12
	s_nop 1
	v_addc_co_u32_e32 v13, vcc, 0, v13, vcc
	global_load_dword v111, v[12:13], off nt
	v_add_co_u32_e32 v12, vcc, 0x3000, v12
	s_nop 1
	v_addc_co_u32_e32 v13, vcc, 0, v13, vcc
	global_load_dword v112, v[12:13], off nt
	v_add_co_u32_e32 v12, vcc, 0x3000, v12
	s_nop 1
	v_addc_co_u32_e32 v13, vcc, 0, v13, vcc
	global_load_dword v113, v[12:13], off nt
	v_add_co_u32_e32 v12, vcc, 0x3000, v12
	s_nop 1
	v_addc_co_u32_e32 v13, vcc, 0, v13, vcc
	global_load_dword v114, v[12:13], off nt
	v_add_co_u32_e32 v12, vcc, 0x3000, v12
	s_nop 1
	v_addc_co_u32_e32 v13, vcc, 0, v13, vcc
	global_load_dword v115, v[12:13], off nt
	v_add_co_u32_e32 v12, vcc, 0x3000, v12
	s_nop 1
	v_addc_co_u32_e32 v13, vcc, 0, v13, vcc
	global_load_dword v116, v[12:13], off nt
	v_add_co_u32_e32 v12, vcc, 0x3000, v12
	s_nop 1
	v_addc_co_u32_e32 v13, vcc, 0, v13, vcc
	global_load_dword v117, v[12:13], off nt
	v_add_co_u32_e32 v12, vcc, 0x3000, v12
	s_nop 1
	v_addc_co_u32_e32 v13, vcc, 0, v13, vcc
	global_load_dword v118, v[12:13], off nt
	v_add_co_u32_e32 v12, vcc, 0x3000, v12
	s_nop 1
	v_addc_co_u32_e32 v13, vcc, 0, v13, vcc
	global_load_dword v119, v[12:13], off nt
	v_add_co_u32_e32 v12, vcc, 0x3000, v12
	s_nop 1
	v_addc_co_u32_e32 v13, vcc, 0, v13, vcc
	global_load_dword v120, v[12:13], off nt
	v_add_co_u32_e32 v12, vcc, 0x3000, v12
	s_nop 1
	v_addc_co_u32_e32 v13, vcc, 0, v13, vcc
	global_load_dword v121, v[12:13], off nt
	v_add_co_u32_e32 v12, vcc, 0x3000, v12
	s_nop 1
	v_addc_co_u32_e32 v13, vcc, 0, v13, vcc
	global_load_dword v122, v[12:13], off nt
	v_add_co_u32_e32 v12, vcc, 0x3000, v12
	s_nop 1
	v_addc_co_u32_e32 v13, vcc, 0, v13, vcc
	global_load_dword v123, v[12:13], off nt
	v_add_co_u32_e32 v12, vcc, 0x3000, v12
	s_nop 1
	v_addc_co_u32_e32 v13, vcc, 0, v13, vcc
	global_load_dword v124, v[12:13], off nt
	v_add_co_u32_e32 v12, vcc, 0x3000, v12
	s_nop 1
	v_addc_co_u32_e32 v13, vcc, 0, v13, vcc
	global_load_dword v125, v[12:13], off nt
	v_add_co_u32_e32 v12, vcc, 0x3000, v12
	s_nop 1
	v_addc_co_u32_e32 v13, vcc, 0, v13, vcc
	global_load_dword v126, v[12:13], off nt
	v_add_co_u32_e32 v12, vcc, 0x3000, v12
	s_nop 1
	v_addc_co_u32_e32 v13, vcc, 0, v13, vcc
	global_load_dword v127, v[12:13], off nt
	v_add_co_u32_e32 v12, vcc, 0x3000, v12
	s_nop 1
	v_addc_co_u32_e32 v13, vcc, 0, v13, vcc
	global_load_dword v128, v[12:13], off nt
	v_add_co_u32_e32 v12, vcc, 0x3000, v12
	s_nop 1
	v_addc_co_u32_e32 v13, vcc, 0, v13, vcc
	global_load_dword v129, v[12:13], off nt
	v_add_co_u32_e32 v12, vcc, 0x3000, v12
	s_nop 1
	v_addc_co_u32_e32 v13, vcc, 0, v13, vcc
	global_load_dword v130, v[12:13], off nt
	v_add_co_u32_e32 v12, vcc, 0x3000, v12
	s_nop 1
	v_addc_co_u32_e32 v13, vcc, 0, v13, vcc
	global_load_dword v131, v[12:13], off nt
	v_add_co_u32_e32 v12, vcc, 0x3000, v12
	s_nop 1
	v_addc_co_u32_e32 v13, vcc, 0, v13, vcc
	global_load_dword v132, v[12:13], off nt
	v_add_co_u32_e32 v12, vcc, 0x3000, v12
	s_nop 1
	v_addc_co_u32_e32 v13, vcc, 0, v13, vcc
	global_load_dword v133, v[12:13], off nt
	v_add_co_u32_e32 v12, vcc, 0x3000, v12
	s_nop 1
	v_addc_co_u32_e32 v13, vcc, 0, v13, vcc
	global_load_dword v134, v[12:13], off nt
	v_add_co_u32_e32 v12, vcc, 0x3000, v12
	s_nop 1
	v_addc_co_u32_e32 v13, vcc, 0, v13, vcc
	global_load_dword v135, v[12:13], off nt
	v_add_co_u32_e32 v12, vcc, 0x3000, v12
	s_nop 1
	v_addc_co_u32_e32 v13, vcc, 0, v13, vcc
	global_load_dword v136, v[12:13], off nt
	v_add_co_u32_e32 v12, vcc, 0x3000, v12
	s_nop 1
	v_addc_co_u32_e32 v13, vcc, 0, v13, vcc
	global_load_dword v137, v[12:13], off nt
	v_add_co_u32_e32 v12, vcc, 0x3000, v12
	s_nop 1
	v_addc_co_u32_e32 v13, vcc, 0, v13, vcc
	global_load_dword v138, v[12:13], off nt
	v_add_co_u32_e32 v12, vcc, 0x3000, v12
	s_nop 1
	v_addc_co_u32_e32 v13, vcc, 0, v13, vcc
	global_load_dword v139, v[12:13], off nt
	v_add_co_u32_e32 v12, vcc, 0x3000, v12
	s_nop 1
	v_addc_co_u32_e32 v13, vcc, 0, v13, vcc
	global_load_dword v140, v[12:13], off nt
	v_add_co_u32_e32 v12, vcc, 0x3000, v12
	s_nop 1
	v_addc_co_u32_e32 v13, vcc, 0, v13, vcc
	global_load_dword v141, v[12:13], off nt
	v_add_co_u32_e32 v12, vcc, 0x3000, v12
	s_nop 1
	v_addc_co_u32_e32 v13, vcc, 0, v13, vcc
	global_load_dword v142, v[12:13], off nt
	v_add_co_u32_e32 v12, vcc, 0x3000, v12
	s_nop 1
	v_addc_co_u32_e32 v13, vcc, 0, v13, vcc
	global_load_dword v143, v[12:13], off nt
	v_add_co_u32_e32 v12, vcc, 0x3000, v12
	s_nop 1
	v_addc_co_u32_e32 v13, vcc, 0, v13, vcc
	global_load_dword v144, v[12:13], off nt
	v_add_co_u32_e32 v12, vcc, 0x3000, v12
	s_nop 1
	v_addc_co_u32_e32 v13, vcc, 0, v13, vcc
	global_load_dword v145, v[12:13], off nt
	v_add_co_u32_e32 v12, vcc, 0x3000, v12
	s_nop 1
	v_addc_co_u32_e32 v13, vcc, 0, v13, vcc
	global_load_dword v146, v[12:13], off nt
	v_add_co_u32_e32 v12, vcc, 0x3000, v12
	s_nop 1
	v_addc_co_u32_e32 v13, vcc, 0, v13, vcc
	global_load_dword v147, v[12:13], off nt
	v_add_co_u32_e32 v12, vcc, 0x3000, v12
	s_nop 1
	v_addc_co_u32_e32 v13, vcc, 0, v13, vcc
	global_load_dword v148, v[12:13], off nt
	v_add_co_u32_e32 v12, vcc, 0x3000, v12
	s_nop 1
	v_addc_co_u32_e32 v13, vcc, 0, v13, vcc
	global_load_dword v149, v[12:13], off nt
	v_add_co_u32_e32 v12, vcc, 0x3000, v12
	s_nop 1
	v_addc_co_u32_e32 v13, vcc, 0, v13, vcc
	global_load_dword v150, v[12:13], off nt
	v_add_co_u32_e32 v12, vcc, 0x3000, v12
	s_nop 1
	v_addc_co_u32_e32 v13, vcc, 0, v13, vcc
	global_load_dword v151, v[12:13], off nt
	v_add_co_u32_e32 v12, vcc, 0x3000, v12
	s_nop 1
	v_addc_co_u32_e32 v13, vcc, 0, v13, vcc
	global_load_dword v152, v[12:13], off nt
	v_add_co_u32_e32 v12, vcc, 0x3000, v12
	s_nop 1
	v_addc_co_u32_e32 v13, vcc, 0, v13, vcc
	global_load_dword v153, v[12:13], off nt
	v_add_co_u32_e32 v12, vcc, 0x3000, v12
	s_nop 1
	v_addc_co_u32_e32 v13, vcc, 0, v13, vcc
	global_load_dword v154, v[12:13], off nt
	v_add_co_u32_e32 v12, vcc, 0x3000, v12
	s_nop 1
	v_addc_co_u32_e32 v13, vcc, 0, v13, vcc
	global_load_dword v155, v[12:13], off nt
	s_waitcnt vmcnt(63)
	v_mul_f32_e32 v166, 0xbfb8aa3b, v156
	v_mul_f32_e32 v167, 0xbfb8aa3b, v157
	v_mul_f32_e32 v168, 0xbfb8aa3b, v158
	v_mul_f32_e32 v169, 0xbfb8aa3b, v159
	v_mul_f32_e32 v170, 0xbfb8aa3b, v160
	v_mul_f32_e32 v171, 0xbfb8aa3b, v161
	v_mul_f32_e32 v172, 0xbfb8aa3b, v162
	v_mul_f32_e32 v173, 0xbfb8aa3b, v163
	v_mul_f32_e32 v174, 0xbfb8aa3b, v164
	v_mul_f32_e32 v175, 0xbfb8aa3b, v165
	v_exp_f32_e32 v166, v166
	v_exp_f32_e32 v167, v167
	v_exp_f32_e32 v168, v168
	v_exp_f32_e32 v169, v169
	v_exp_f32_e32 v170, v170
	v_exp_f32_e32 v171, v171
	v_exp_f32_e32 v172, v172
	v_exp_f32_e32 v173, v173
	v_exp_f32_e32 v174, v174
	v_exp_f32_e32 v175, v175
	v_add_f32_e32 v166, 1.0, v166
	v_add_f32_e32 v167, 1.0, v167
	v_add_f32_e32 v168, 1.0, v168
	v_add_f32_e32 v169, 1.0, v169
	v_add_f32_e32 v170, 1.0, v170
	v_add_f32_e32 v171, 1.0, v171
	v_add_f32_e32 v172, 1.0, v172
	v_add_f32_e32 v173, 1.0, v173
	v_add_f32_e32 v174, 1.0, v174
	v_add_f32_e32 v175, 1.0, v175
	v_rcp_f32_e32 v166, v166
	v_rcp_f32_e32 v167, v167
	v_rcp_f32_e32 v168, v168
	v_rcp_f32_e32 v169, v169
	v_rcp_f32_e32 v170, v170
	v_rcp_f32_e32 v171, v171
	v_rcp_f32_e32 v172, v172
	v_rcp_f32_e32 v173, v173
	v_rcp_f32_e32 v174, v174
	v_rcp_f32_e32 v175, v175
	v_mul_f32_e32 v156, v156, v166
	v_mul_f32_e32 v157, v157, v167
	v_mul_f32_e32 v158, v158, v168
	v_mul_f32_e32 v159, v159, v169
	v_mul_f32_e32 v160, v160, v170
	v_mul_f32_e32 v161, v161, v171
	v_mul_f32_e32 v162, v162, v172
	v_mul_f32_e32 v163, v163, v173
	v_mul_f32_e32 v164, v164, v174
	v_mul_f32_e32 v165, v165, v175
	v_readlane_b32 s12, v156, 0
	v_readlane_b32 s13, v157, 0
	v_readlane_b32 s14, v158, 0
	v_readlane_b32 s15, v159, 0
	v_readlane_b32 s16, v160, 0
	s_waitcnt vmcnt(63)
	v_pk_fma_f32 v[10:11], v[28:29], s[12:13], v[10:11] op_sel_hi:[0,1,1]
	v_pk_fma_f32 v[8:9], v[28:29], s[14:15], v[8:9] op_sel_hi:[0,1,1]
	v_fmac_f32_e32 v22, s16, v28
	v_readlane_b32 s12, v156, 1
	v_readlane_b32 s13, v157, 1
	v_readlane_b32 s14, v158, 1
	v_readlane_b32 s15, v159, 1
	v_readlane_b32 s16, v160, 1
	s_waitcnt vmcnt(63)
	v_pk_fma_f32 v[10:11], v[28:29], s[12:13], v[10:11] op_sel:[1,0,0] op_sel_hi:[1,1,1]
	v_pk_fma_f32 v[8:9], v[28:29], s[14:15], v[8:9] op_sel:[1,0,0] op_sel_hi:[1,1,1]
	v_fmac_f32_e32 v22, s16, v29
	v_readlane_b32 s12, v156, 2
	v_readlane_b32 s13, v157, 2
	v_readlane_b32 s14, v158, 2
	v_readlane_b32 s15, v159, 2
	v_readlane_b32 s16, v160, 2
	s_waitcnt vmcnt(63)
	v_pk_fma_f32 v[10:11], v[30:31], s[12:13], v[10:11] op_sel_hi:[0,1,1]
	v_pk_fma_f32 v[8:9], v[30:31], s[14:15], v[8:9] op_sel_hi:[0,1,1]
	v_fmac_f32_e32 v22, s16, v30
	v_readlane_b32 s12, v156, 3
	v_readlane_b32 s13, v157, 3
	v_readlane_b32 s14, v158, 3
	v_readlane_b32 s15, v159, 3
	v_readlane_b32 s16, v160, 3
	s_waitcnt vmcnt(63)
	v_pk_fma_f32 v[10:11], v[30:31], s[12:13], v[10:11] op_sel:[1,0,0] op_sel_hi:[1,1,1]
	v_pk_fma_f32 v[8:9], v[30:31], s[14:15], v[8:9] op_sel:[1,0,0] op_sel_hi:[1,1,1]
	v_fmac_f32_e32 v22, s16, v31
	v_readlane_b32 s12, v156, 4
	v_readlane_b32 s13, v157, 4
	v_readlane_b32 s14, v158, 4
	v_readlane_b32 s15, v159, 4
	v_readlane_b32 s16, v160, 4
	s_waitcnt vmcnt(63)
	v_pk_fma_f32 v[10:11], v[32:33], s[12:13], v[10:11] op_sel_hi:[0,1,1]
	v_pk_fma_f32 v[8:9], v[32:33], s[14:15], v[8:9] op_sel_hi:[0,1,1]
	v_fmac_f32_e32 v22, s16, v32
	v_readlane_b32 s12, v156, 5
	v_readlane_b32 s13, v157, 5
	v_readlane_b32 s14, v158, 5
	v_readlane_b32 s15, v159, 5
	v_readlane_b32 s16, v160, 5
	s_waitcnt vmcnt(63)
	v_pk_fma_f32 v[10:11], v[32:33], s[12:13], v[10:11] op_sel:[1,0,0] op_sel_hi:[1,1,1]
	v_pk_fma_f32 v[8:9], v[32:33], s[14:15], v[8:9] op_sel:[1,0,0] op_sel_hi:[1,1,1]
	v_fmac_f32_e32 v22, s16, v33
	v_readlane_b32 s12, v156, 6
	v_readlane_b32 s13, v157, 6
	v_readlane_b32 s14, v158, 6
	v_readlane_b32 s15, v159, 6
	v_readlane_b32 s16, v160, 6
	s_waitcnt vmcnt(63)
	v_pk_fma_f32 v[10:11], v[34:35], s[12:13], v[10:11] op_sel_hi:[0,1,1]
	v_pk_fma_f32 v[8:9], v[34:35], s[14:15], v[8:9] op_sel_hi:[0,1,1]
	v_fmac_f32_e32 v22, s16, v34
	v_readlane_b32 s12, v156, 7
	v_readlane_b32 s13, v157, 7
	v_readlane_b32 s14, v158, 7
	v_readlane_b32 s15, v159, 7
	v_readlane_b32 s16, v160, 7
	s_waitcnt vmcnt(63)
	v_pk_fma_f32 v[10:11], v[34:35], s[12:13], v[10:11] op_sel:[1,0,0] op_sel_hi:[1,1,1]
	v_pk_fma_f32 v[8:9], v[34:35], s[14:15], v[8:9] op_sel:[1,0,0] op_sel_hi:[1,1,1]
	v_fmac_f32_e32 v22, s16, v35
	v_readlane_b32 s12, v156, 8
	v_readlane_b32 s13, v157, 8
	v_readlane_b32 s14, v158, 8
	v_readlane_b32 s15, v159, 8
	v_readlane_b32 s16, v160, 8
	s_waitcnt vmcnt(63)
	v_pk_fma_f32 v[10:11], v[36:37], s[12:13], v[10:11] op_sel_hi:[0,1,1]
	v_pk_fma_f32 v[8:9], v[36:37], s[14:15], v[8:9] op_sel_hi:[0,1,1]
	v_fmac_f32_e32 v22, s16, v36
	v_readlane_b32 s12, v156, 9
	v_readlane_b32 s13, v157, 9
	v_readlane_b32 s14, v158, 9
	v_readlane_b32 s15, v159, 9
	v_readlane_b32 s16, v160, 9
	s_waitcnt vmcnt(63)
	v_pk_fma_f32 v[10:11], v[36:37], s[12:13], v[10:11] op_sel:[1,0,0] op_sel_hi:[1,1,1]
	v_pk_fma_f32 v[8:9], v[36:37], s[14:15], v[8:9] op_sel:[1,0,0] op_sel_hi:[1,1,1]
	v_fmac_f32_e32 v22, s16, v37
	v_readlane_b32 s12, v156, 10
	v_readlane_b32 s13, v157, 10
	v_readlane_b32 s14, v158, 10
	v_readlane_b32 s15, v159, 10
	v_readlane_b32 s16, v160, 10
	s_waitcnt vmcnt(63)
	v_pk_fma_f32 v[10:11], v[38:39], s[12:13], v[10:11] op_sel_hi:[0,1,1]
	v_pk_fma_f32 v[8:9], v[38:39], s[14:15], v[8:9] op_sel_hi:[0,1,1]
	v_fmac_f32_e32 v22, s16, v38
	v_readlane_b32 s12, v156, 11
	v_readlane_b32 s13, v157, 11
	v_readlane_b32 s14, v158, 11
	v_readlane_b32 s15, v159, 11
	v_readlane_b32 s16, v160, 11
	s_waitcnt vmcnt(63)
	v_pk_fma_f32 v[10:11], v[38:39], s[12:13], v[10:11] op_sel:[1,0,0] op_sel_hi:[1,1,1]
	v_pk_fma_f32 v[8:9], v[38:39], s[14:15], v[8:9] op_sel:[1,0,0] op_sel_hi:[1,1,1]
	v_fmac_f32_e32 v22, s16, v39
	v_readlane_b32 s12, v156, 12
	v_readlane_b32 s13, v157, 12
	v_readlane_b32 s14, v158, 12
	v_readlane_b32 s15, v159, 12
	v_readlane_b32 s16, v160, 12
	s_waitcnt vmcnt(63)
	v_pk_fma_f32 v[10:11], v[40:41], s[12:13], v[10:11] op_sel_hi:[0,1,1]
	v_pk_fma_f32 v[8:9], v[40:41], s[14:15], v[8:9] op_sel_hi:[0,1,1]
	v_fmac_f32_e32 v22, s16, v40
	v_readlane_b32 s12, v156, 13
	v_readlane_b32 s13, v157, 13
	v_readlane_b32 s14, v158, 13
	v_readlane_b32 s15, v159, 13
	v_readlane_b32 s16, v160, 13
	s_waitcnt vmcnt(63)
	v_pk_fma_f32 v[10:11], v[40:41], s[12:13], v[10:11] op_sel:[1,0,0] op_sel_hi:[1,1,1]
	v_pk_fma_f32 v[8:9], v[40:41], s[14:15], v[8:9] op_sel:[1,0,0] op_sel_hi:[1,1,1]
	v_fmac_f32_e32 v22, s16, v41
	v_readlane_b32 s12, v156, 14
	v_readlane_b32 s13, v157, 14
	v_readlane_b32 s14, v158, 14
	v_readlane_b32 s15, v159, 14
	v_readlane_b32 s16, v160, 14
	s_waitcnt vmcnt(63)
	v_pk_fma_f32 v[10:11], v[42:43], s[12:13], v[10:11] op_sel_hi:[0,1,1]
	v_pk_fma_f32 v[8:9], v[42:43], s[14:15], v[8:9] op_sel_hi:[0,1,1]
	v_fmac_f32_e32 v22, s16, v42
	v_readlane_b32 s12, v156, 15
	v_readlane_b32 s13, v157, 15
	v_readlane_b32 s14, v158, 15
	v_readlane_b32 s15, v159, 15
	v_readlane_b32 s16, v160, 15
	s_waitcnt vmcnt(63)
	v_pk_fma_f32 v[10:11], v[42:43], s[12:13], v[10:11] op_sel:[1,0,0] op_sel_hi:[1,1,1]
	v_pk_fma_f32 v[8:9], v[42:43], s[14:15], v[8:9] op_sel:[1,0,0] op_sel_hi:[1,1,1]
	v_fmac_f32_e32 v22, s16, v43
	v_readlane_b32 s12, v156, 16
	v_readlane_b32 s13, v157, 16
	v_readlane_b32 s14, v158, 16
	v_readlane_b32 s15, v159, 16
	v_readlane_b32 s16, v160, 16
	s_waitcnt vmcnt(63)
	v_pk_fma_f32 v[10:11], v[44:45], s[12:13], v[10:11] op_sel_hi:[0,1,1]
	v_pk_fma_f32 v[8:9], v[44:45], s[14:15], v[8:9] op_sel_hi:[0,1,1]
	v_fmac_f32_e32 v22, s16, v44
	v_readlane_b32 s12, v156, 17
	v_readlane_b32 s13, v157, 17
	v_readlane_b32 s14, v158, 17
	v_readlane_b32 s15, v159, 17
	v_readlane_b32 s16, v160, 17
	s_waitcnt vmcnt(63)
	v_pk_fma_f32 v[10:11], v[44:45], s[12:13], v[10:11] op_sel:[1,0,0] op_sel_hi:[1,1,1]
	v_pk_fma_f32 v[8:9], v[44:45], s[14:15], v[8:9] op_sel:[1,0,0] op_sel_hi:[1,1,1]
	v_fmac_f32_e32 v22, s16, v45
	v_readlane_b32 s12, v156, 18
	v_readlane_b32 s13, v157, 18
	v_readlane_b32 s14, v158, 18
	v_readlane_b32 s15, v159, 18
	v_readlane_b32 s16, v160, 18
	s_waitcnt vmcnt(63)
	v_pk_fma_f32 v[10:11], v[46:47], s[12:13], v[10:11] op_sel_hi:[0,1,1]
	v_pk_fma_f32 v[8:9], v[46:47], s[14:15], v[8:9] op_sel_hi:[0,1,1]
	v_fmac_f32_e32 v22, s16, v46
	v_readlane_b32 s12, v156, 19
	v_readlane_b32 s13, v157, 19
	v_readlane_b32 s14, v158, 19
	v_readlane_b32 s15, v159, 19
	v_readlane_b32 s16, v160, 19
	s_waitcnt vmcnt(63)
	v_pk_fma_f32 v[10:11], v[46:47], s[12:13], v[10:11] op_sel:[1,0,0] op_sel_hi:[1,1,1]
	v_pk_fma_f32 v[8:9], v[46:47], s[14:15], v[8:9] op_sel:[1,0,0] op_sel_hi:[1,1,1]
	v_fmac_f32_e32 v22, s16, v47
	v_readlane_b32 s12, v156, 20
	v_readlane_b32 s13, v157, 20
	v_readlane_b32 s14, v158, 20
	v_readlane_b32 s15, v159, 20
	v_readlane_b32 s16, v160, 20
	s_waitcnt vmcnt(63)
	v_pk_fma_f32 v[10:11], v[48:49], s[12:13], v[10:11] op_sel_hi:[0,1,1]
	v_pk_fma_f32 v[8:9], v[48:49], s[14:15], v[8:9] op_sel_hi:[0,1,1]
	v_fmac_f32_e32 v22, s16, v48
	v_readlane_b32 s12, v156, 21
	v_readlane_b32 s13, v157, 21
	v_readlane_b32 s14, v158, 21
	v_readlane_b32 s15, v159, 21
	v_readlane_b32 s16, v160, 21
	s_waitcnt vmcnt(63)
	v_pk_fma_f32 v[10:11], v[48:49], s[12:13], v[10:11] op_sel:[1,0,0] op_sel_hi:[1,1,1]
	v_pk_fma_f32 v[8:9], v[48:49], s[14:15], v[8:9] op_sel:[1,0,0] op_sel_hi:[1,1,1]
	v_fmac_f32_e32 v22, s16, v49
	v_readlane_b32 s12, v156, 22
	v_readlane_b32 s13, v157, 22
	v_readlane_b32 s14, v158, 22
	v_readlane_b32 s15, v159, 22
	v_readlane_b32 s16, v160, 22
	s_waitcnt vmcnt(63)
	v_pk_fma_f32 v[10:11], v[50:51], s[12:13], v[10:11] op_sel_hi:[0,1,1]
	v_pk_fma_f32 v[8:9], v[50:51], s[14:15], v[8:9] op_sel_hi:[0,1,1]
	v_fmac_f32_e32 v22, s16, v50
	v_readlane_b32 s12, v156, 23
	v_readlane_b32 s13, v157, 23
	v_readlane_b32 s14, v158, 23
	v_readlane_b32 s15, v159, 23
	v_readlane_b32 s16, v160, 23
	s_waitcnt vmcnt(63)
	v_pk_fma_f32 v[10:11], v[50:51], s[12:13], v[10:11] op_sel:[1,0,0] op_sel_hi:[1,1,1]
	v_pk_fma_f32 v[8:9], v[50:51], s[14:15], v[8:9] op_sel:[1,0,0] op_sel_hi:[1,1,1]
	v_fmac_f32_e32 v22, s16, v51
	v_readlane_b32 s12, v156, 24
	v_readlane_b32 s13, v157, 24
	v_readlane_b32 s14, v158, 24
	v_readlane_b32 s15, v159, 24
	v_readlane_b32 s16, v160, 24
	s_waitcnt vmcnt(63)
	v_pk_fma_f32 v[10:11], v[52:53], s[12:13], v[10:11] op_sel_hi:[0,1,1]
	v_pk_fma_f32 v[8:9], v[52:53], s[14:15], v[8:9] op_sel_hi:[0,1,1]
	v_fmac_f32_e32 v22, s16, v52
	v_readlane_b32 s12, v156, 25
	v_readlane_b32 s13, v157, 25
	v_readlane_b32 s14, v158, 25
	v_readlane_b32 s15, v159, 25
	v_readlane_b32 s16, v160, 25
	s_waitcnt vmcnt(63)
	v_pk_fma_f32 v[10:11], v[52:53], s[12:13], v[10:11] op_sel:[1,0,0] op_sel_hi:[1,1,1]
	v_pk_fma_f32 v[8:9], v[52:53], s[14:15], v[8:9] op_sel:[1,0,0] op_sel_hi:[1,1,1]
	v_fmac_f32_e32 v22, s16, v53
	v_readlane_b32 s12, v156, 26
	v_readlane_b32 s13, v157, 26
	v_readlane_b32 s14, v158, 26
	v_readlane_b32 s15, v159, 26
	v_readlane_b32 s16, v160, 26
	s_waitcnt vmcnt(63)
	v_pk_fma_f32 v[10:11], v[54:55], s[12:13], v[10:11] op_sel_hi:[0,1,1]
	v_pk_fma_f32 v[8:9], v[54:55], s[14:15], v[8:9] op_sel_hi:[0,1,1]
	v_fmac_f32_e32 v22, s16, v54
	v_readlane_b32 s12, v156, 27
	v_readlane_b32 s13, v157, 27
	v_readlane_b32 s14, v158, 27
	v_readlane_b32 s15, v159, 27
	v_readlane_b32 s16, v160, 27
	s_waitcnt vmcnt(63)
	v_pk_fma_f32 v[10:11], v[54:55], s[12:13], v[10:11] op_sel:[1,0,0] op_sel_hi:[1,1,1]
	v_pk_fma_f32 v[8:9], v[54:55], s[14:15], v[8:9] op_sel:[1,0,0] op_sel_hi:[1,1,1]
	v_fmac_f32_e32 v22, s16, v55
	v_readlane_b32 s12, v156, 28
	v_readlane_b32 s13, v157, 28
	v_readlane_b32 s14, v158, 28
	v_readlane_b32 s15, v159, 28
	v_readlane_b32 s16, v160, 28
	s_waitcnt vmcnt(63)
	v_pk_fma_f32 v[10:11], v[56:57], s[12:13], v[10:11] op_sel_hi:[0,1,1]
	v_pk_fma_f32 v[8:9], v[56:57], s[14:15], v[8:9] op_sel_hi:[0,1,1]
	v_fmac_f32_e32 v22, s16, v56
	v_readlane_b32 s12, v156, 29
	v_readlane_b32 s13, v157, 29
	v_readlane_b32 s14, v158, 29
	v_readlane_b32 s15, v159, 29
	v_readlane_b32 s16, v160, 29
	s_waitcnt vmcnt(63)
	v_pk_fma_f32 v[10:11], v[56:57], s[12:13], v[10:11] op_sel:[1,0,0] op_sel_hi:[1,1,1]
	v_pk_fma_f32 v[8:9], v[56:57], s[14:15], v[8:9] op_sel:[1,0,0] op_sel_hi:[1,1,1]
	v_fmac_f32_e32 v22, s16, v57
	v_readlane_b32 s12, v156, 30
	v_readlane_b32 s13, v157, 30
	v_readlane_b32 s14, v158, 30
	v_readlane_b32 s15, v159, 30
	v_readlane_b32 s16, v160, 30
	s_waitcnt vmcnt(63)
	v_pk_fma_f32 v[10:11], v[58:59], s[12:13], v[10:11] op_sel_hi:[0,1,1]
	v_pk_fma_f32 v[8:9], v[58:59], s[14:15], v[8:9] op_sel_hi:[0,1,1]
	v_fmac_f32_e32 v22, s16, v58
	v_readlane_b32 s12, v156, 31
	v_readlane_b32 s13, v157, 31
	v_readlane_b32 s14, v158, 31
	v_readlane_b32 s15, v159, 31
	v_readlane_b32 s16, v160, 31
	s_waitcnt vmcnt(63)
	v_pk_fma_f32 v[10:11], v[58:59], s[12:13], v[10:11] op_sel:[1,0,0] op_sel_hi:[1,1,1]
	v_pk_fma_f32 v[8:9], v[58:59], s[14:15], v[8:9] op_sel:[1,0,0] op_sel_hi:[1,1,1]
	v_fmac_f32_e32 v22, s16, v59
	v_readlane_b32 s12, v156, 32
	v_readlane_b32 s13, v157, 32
	v_readlane_b32 s14, v158, 32
	v_readlane_b32 s15, v159, 32
	v_readlane_b32 s16, v160, 32
	s_waitcnt vmcnt(63)
	v_pk_fma_f32 v[10:11], v[60:61], s[12:13], v[10:11] op_sel_hi:[0,1,1]
	v_pk_fma_f32 v[8:9], v[60:61], s[14:15], v[8:9] op_sel_hi:[0,1,1]
	v_fmac_f32_e32 v22, s16, v60
	v_readlane_b32 s12, v156, 33
	v_readlane_b32 s13, v157, 33
	v_readlane_b32 s14, v158, 33
	v_readlane_b32 s15, v159, 33
	v_readlane_b32 s16, v160, 33
	s_waitcnt vmcnt(63)
	v_pk_fma_f32 v[10:11], v[60:61], s[12:13], v[10:11] op_sel:[1,0,0] op_sel_hi:[1,1,1]
	v_pk_fma_f32 v[8:9], v[60:61], s[14:15], v[8:9] op_sel:[1,0,0] op_sel_hi:[1,1,1]
	v_fmac_f32_e32 v22, s16, v61
	v_readlane_b32 s12, v156, 34
	v_readlane_b32 s13, v157, 34
	v_readlane_b32 s14, v158, 34
	v_readlane_b32 s15, v159, 34
	v_readlane_b32 s16, v160, 34
	s_waitcnt vmcnt(63)
	v_pk_fma_f32 v[10:11], v[62:63], s[12:13], v[10:11] op_sel_hi:[0,1,1]
	v_pk_fma_f32 v[8:9], v[62:63], s[14:15], v[8:9] op_sel_hi:[0,1,1]
	v_fmac_f32_e32 v22, s16, v62
	v_readlane_b32 s12, v156, 35
	v_readlane_b32 s13, v157, 35
	v_readlane_b32 s14, v158, 35
	v_readlane_b32 s15, v159, 35
	v_readlane_b32 s16, v160, 35
	s_waitcnt vmcnt(63)
	v_pk_fma_f32 v[10:11], v[62:63], s[12:13], v[10:11] op_sel:[1,0,0] op_sel_hi:[1,1,1]
	v_pk_fma_f32 v[8:9], v[62:63], s[14:15], v[8:9] op_sel:[1,0,0] op_sel_hi:[1,1,1]
	v_fmac_f32_e32 v22, s16, v63
	v_readlane_b32 s12, v156, 36
	v_readlane_b32 s13, v157, 36
	v_readlane_b32 s14, v158, 36
	v_readlane_b32 s15, v159, 36
	v_readlane_b32 s16, v160, 36
	s_waitcnt vmcnt(63)
	v_pk_fma_f32 v[10:11], v[64:65], s[12:13], v[10:11] op_sel_hi:[0,1,1]
	v_pk_fma_f32 v[8:9], v[64:65], s[14:15], v[8:9] op_sel_hi:[0,1,1]
	v_fmac_f32_e32 v22, s16, v64
	v_readlane_b32 s12, v156, 37
	v_readlane_b32 s13, v157, 37
	v_readlane_b32 s14, v158, 37
	v_readlane_b32 s15, v159, 37
	v_readlane_b32 s16, v160, 37
	s_waitcnt vmcnt(63)
	v_pk_fma_f32 v[10:11], v[64:65], s[12:13], v[10:11] op_sel:[1,0,0] op_sel_hi:[1,1,1]
	v_pk_fma_f32 v[8:9], v[64:65], s[14:15], v[8:9] op_sel:[1,0,0] op_sel_hi:[1,1,1]
	v_fmac_f32_e32 v22, s16, v65
	v_readlane_b32 s12, v156, 38
	v_readlane_b32 s13, v157, 38
	v_readlane_b32 s14, v158, 38
	v_readlane_b32 s15, v159, 38
	v_readlane_b32 s16, v160, 38
	s_waitcnt vmcnt(63)
	v_pk_fma_f32 v[10:11], v[66:67], s[12:13], v[10:11] op_sel_hi:[0,1,1]
	v_pk_fma_f32 v[8:9], v[66:67], s[14:15], v[8:9] op_sel_hi:[0,1,1]
	v_fmac_f32_e32 v22, s16, v66
	v_readlane_b32 s12, v156, 39
	v_readlane_b32 s13, v157, 39
	v_readlane_b32 s14, v158, 39
	v_readlane_b32 s15, v159, 39
	v_readlane_b32 s16, v160, 39
	s_waitcnt vmcnt(63)
	v_pk_fma_f32 v[10:11], v[66:67], s[12:13], v[10:11] op_sel:[1,0,0] op_sel_hi:[1,1,1]
	v_pk_fma_f32 v[8:9], v[66:67], s[14:15], v[8:9] op_sel:[1,0,0] op_sel_hi:[1,1,1]
	v_fmac_f32_e32 v22, s16, v67
	v_readlane_b32 s12, v156, 40
	v_readlane_b32 s13, v157, 40
	v_readlane_b32 s14, v158, 40
	v_readlane_b32 s15, v159, 40
	v_readlane_b32 s16, v160, 40
	s_waitcnt vmcnt(63)
	v_pk_fma_f32 v[10:11], v[68:69], s[12:13], v[10:11] op_sel_hi:[0,1,1]
	v_pk_fma_f32 v[8:9], v[68:69], s[14:15], v[8:9] op_sel_hi:[0,1,1]
	v_fmac_f32_e32 v22, s16, v68
	v_readlane_b32 s12, v156, 41
	v_readlane_b32 s13, v157, 41
	v_readlane_b32 s14, v158, 41
	v_readlane_b32 s15, v159, 41
	v_readlane_b32 s16, v160, 41
	s_waitcnt vmcnt(63)
	v_pk_fma_f32 v[10:11], v[68:69], s[12:13], v[10:11] op_sel:[1,0,0] op_sel_hi:[1,1,1]
	v_pk_fma_f32 v[8:9], v[68:69], s[14:15], v[8:9] op_sel:[1,0,0] op_sel_hi:[1,1,1]
	v_fmac_f32_e32 v22, s16, v69
	v_readlane_b32 s12, v156, 42
	v_readlane_b32 s13, v157, 42
	v_readlane_b32 s14, v158, 42
	v_readlane_b32 s15, v159, 42
	v_readlane_b32 s16, v160, 42
	s_waitcnt vmcnt(63)
	v_pk_fma_f32 v[10:11], v[70:71], s[12:13], v[10:11] op_sel_hi:[0,1,1]
	v_pk_fma_f32 v[8:9], v[70:71], s[14:15], v[8:9] op_sel_hi:[0,1,1]
	v_fmac_f32_e32 v22, s16, v70
	v_readlane_b32 s12, v156, 43
	v_readlane_b32 s13, v157, 43
	v_readlane_b32 s14, v158, 43
	v_readlane_b32 s15, v159, 43
	v_readlane_b32 s16, v160, 43
	s_waitcnt vmcnt(63)
	v_pk_fma_f32 v[10:11], v[70:71], s[12:13], v[10:11] op_sel:[1,0,0] op_sel_hi:[1,1,1]
	v_pk_fma_f32 v[8:9], v[70:71], s[14:15], v[8:9] op_sel:[1,0,0] op_sel_hi:[1,1,1]
	v_fmac_f32_e32 v22, s16, v71
	v_readlane_b32 s12, v156, 44
	v_readlane_b32 s13, v157, 44
	v_readlane_b32 s14, v158, 44
	v_readlane_b32 s15, v159, 44
	v_readlane_b32 s16, v160, 44
	s_waitcnt vmcnt(63)
	v_pk_fma_f32 v[10:11], v[72:73], s[12:13], v[10:11] op_sel_hi:[0,1,1]
	v_pk_fma_f32 v[8:9], v[72:73], s[14:15], v[8:9] op_sel_hi:[0,1,1]
	v_fmac_f32_e32 v22, s16, v72
	v_readlane_b32 s12, v156, 45
	v_readlane_b32 s13, v157, 45
	v_readlane_b32 s14, v158, 45
	v_readlane_b32 s15, v159, 45
	v_readlane_b32 s16, v160, 45
	s_waitcnt vmcnt(63)
	v_pk_fma_f32 v[10:11], v[72:73], s[12:13], v[10:11] op_sel:[1,0,0] op_sel_hi:[1,1,1]
	v_pk_fma_f32 v[8:9], v[72:73], s[14:15], v[8:9] op_sel:[1,0,0] op_sel_hi:[1,1,1]
	v_fmac_f32_e32 v22, s16, v73
	v_readlane_b32 s12, v156, 46
	v_readlane_b32 s13, v157, 46
	v_readlane_b32 s14, v158, 46
	v_readlane_b32 s15, v159, 46
	v_readlane_b32 s16, v160, 46
	s_waitcnt vmcnt(63)
	v_pk_fma_f32 v[10:11], v[74:75], s[12:13], v[10:11] op_sel_hi:[0,1,1]
	v_pk_fma_f32 v[8:9], v[74:75], s[14:15], v[8:9] op_sel_hi:[0,1,1]
	v_fmac_f32_e32 v22, s16, v74
	v_readlane_b32 s12, v156, 47
	v_readlane_b32 s13, v157, 47
	v_readlane_b32 s14, v158, 47
	v_readlane_b32 s15, v159, 47
	v_readlane_b32 s16, v160, 47
	s_waitcnt vmcnt(63)
	v_pk_fma_f32 v[10:11], v[74:75], s[12:13], v[10:11] op_sel:[1,0,0] op_sel_hi:[1,1,1]
	v_pk_fma_f32 v[8:9], v[74:75], s[14:15], v[8:9] op_sel:[1,0,0] op_sel_hi:[1,1,1]
	v_fmac_f32_e32 v22, s16, v75
	v_readlane_b32 s12, v156, 48
	v_readlane_b32 s13, v157, 48
	v_readlane_b32 s14, v158, 48
	v_readlane_b32 s15, v159, 48
	v_readlane_b32 s16, v160, 48
	s_waitcnt vmcnt(63)
	v_pk_fma_f32 v[10:11], v[76:77], s[12:13], v[10:11] op_sel_hi:[0,1,1]
	v_pk_fma_f32 v[8:9], v[76:77], s[14:15], v[8:9] op_sel_hi:[0,1,1]
	v_fmac_f32_e32 v22, s16, v76
	v_readlane_b32 s12, v156, 49
	v_readlane_b32 s13, v157, 49
	v_readlane_b32 s14, v158, 49
	v_readlane_b32 s15, v159, 49
	v_readlane_b32 s16, v160, 49
	s_waitcnt vmcnt(63)
	v_pk_fma_f32 v[10:11], v[76:77], s[12:13], v[10:11] op_sel:[1,0,0] op_sel_hi:[1,1,1]
	v_pk_fma_f32 v[8:9], v[76:77], s[14:15], v[8:9] op_sel:[1,0,0] op_sel_hi:[1,1,1]
	v_fmac_f32_e32 v22, s16, v77
	v_readlane_b32 s12, v156, 50
	v_readlane_b32 s13, v157, 50
	v_readlane_b32 s14, v158, 50
	v_readlane_b32 s15, v159, 50
	v_readlane_b32 s16, v160, 50
	s_waitcnt vmcnt(63)
	v_pk_fma_f32 v[10:11], v[78:79], s[12:13], v[10:11] op_sel_hi:[0,1,1]
	v_pk_fma_f32 v[8:9], v[78:79], s[14:15], v[8:9] op_sel_hi:[0,1,1]
	v_fmac_f32_e32 v22, s16, v78
	v_readlane_b32 s12, v156, 51
	v_readlane_b32 s13, v157, 51
	v_readlane_b32 s14, v158, 51
	v_readlane_b32 s15, v159, 51
	v_readlane_b32 s16, v160, 51
	s_waitcnt vmcnt(63)
	v_pk_fma_f32 v[10:11], v[78:79], s[12:13], v[10:11] op_sel:[1,0,0] op_sel_hi:[1,1,1]
	v_pk_fma_f32 v[8:9], v[78:79], s[14:15], v[8:9] op_sel:[1,0,0] op_sel_hi:[1,1,1]
	v_fmac_f32_e32 v22, s16, v79
	v_readlane_b32 s12, v156, 52
	v_readlane_b32 s13, v157, 52
	v_readlane_b32 s14, v158, 52
	v_readlane_b32 s15, v159, 52
	v_readlane_b32 s16, v160, 52
	s_waitcnt vmcnt(63)
	v_pk_fma_f32 v[10:11], v[80:81], s[12:13], v[10:11] op_sel_hi:[0,1,1]
	v_pk_fma_f32 v[8:9], v[80:81], s[14:15], v[8:9] op_sel_hi:[0,1,1]
	v_fmac_f32_e32 v22, s16, v80
	v_readlane_b32 s12, v156, 53
	v_readlane_b32 s13, v157, 53
	v_readlane_b32 s14, v158, 53
	v_readlane_b32 s15, v159, 53
	v_readlane_b32 s16, v160, 53
	s_waitcnt vmcnt(63)
	v_pk_fma_f32 v[10:11], v[80:81], s[12:13], v[10:11] op_sel:[1,0,0] op_sel_hi:[1,1,1]
	v_pk_fma_f32 v[8:9], v[80:81], s[14:15], v[8:9] op_sel:[1,0,0] op_sel_hi:[1,1,1]
	v_fmac_f32_e32 v22, s16, v81
	v_readlane_b32 s12, v156, 54
	v_readlane_b32 s13, v157, 54
	v_readlane_b32 s14, v158, 54
	v_readlane_b32 s15, v159, 54
	v_readlane_b32 s16, v160, 54
	s_waitcnt vmcnt(63)
	v_pk_fma_f32 v[10:11], v[82:83], s[12:13], v[10:11] op_sel_hi:[0,1,1]
	v_pk_fma_f32 v[8:9], v[82:83], s[14:15], v[8:9] op_sel_hi:[0,1,1]
	v_fmac_f32_e32 v22, s16, v82
	v_readlane_b32 s12, v156, 55
	v_readlane_b32 s13, v157, 55
	v_readlane_b32 s14, v158, 55
	v_readlane_b32 s15, v159, 55
	v_readlane_b32 s16, v160, 55
	s_waitcnt vmcnt(63)
	v_pk_fma_f32 v[10:11], v[82:83], s[12:13], v[10:11] op_sel:[1,0,0] op_sel_hi:[1,1,1]
	v_pk_fma_f32 v[8:9], v[82:83], s[14:15], v[8:9] op_sel:[1,0,0] op_sel_hi:[1,1,1]
	v_fmac_f32_e32 v22, s16, v83
	v_readlane_b32 s12, v156, 56
	v_readlane_b32 s13, v157, 56
	v_readlane_b32 s14, v158, 56
	v_readlane_b32 s15, v159, 56
	v_readlane_b32 s16, v160, 56
	s_waitcnt vmcnt(63)
	v_pk_fma_f32 v[10:11], v[84:85], s[12:13], v[10:11] op_sel_hi:[0,1,1]
	v_pk_fma_f32 v[8:9], v[84:85], s[14:15], v[8:9] op_sel_hi:[0,1,1]
	v_fmac_f32_e32 v22, s16, v84
	v_readlane_b32 s12, v156, 57
	v_readlane_b32 s13, v157, 57
	v_readlane_b32 s14, v158, 57
	v_readlane_b32 s15, v159, 57
	v_readlane_b32 s16, v160, 57
	s_waitcnt vmcnt(63)
	v_pk_fma_f32 v[10:11], v[84:85], s[12:13], v[10:11] op_sel:[1,0,0] op_sel_hi:[1,1,1]
	v_pk_fma_f32 v[8:9], v[84:85], s[14:15], v[8:9] op_sel:[1,0,0] op_sel_hi:[1,1,1]
	v_fmac_f32_e32 v22, s16, v85
	v_readlane_b32 s12, v156, 58
	v_readlane_b32 s13, v157, 58
	v_readlane_b32 s14, v158, 58
	v_readlane_b32 s15, v159, 58
	v_readlane_b32 s16, v160, 58
	s_waitcnt vmcnt(63)
	v_pk_fma_f32 v[10:11], v[86:87], s[12:13], v[10:11] op_sel_hi:[0,1,1]
	v_pk_fma_f32 v[8:9], v[86:87], s[14:15], v[8:9] op_sel_hi:[0,1,1]
	v_fmac_f32_e32 v22, s16, v86
	v_readlane_b32 s12, v156, 59
	v_readlane_b32 s13, v157, 59
	v_readlane_b32 s14, v158, 59
	v_readlane_b32 s15, v159, 59
	v_readlane_b32 s16, v160, 59
	s_waitcnt vmcnt(63)
	v_pk_fma_f32 v[10:11], v[86:87], s[12:13], v[10:11] op_sel:[1,0,0] op_sel_hi:[1,1,1]
	v_pk_fma_f32 v[8:9], v[86:87], s[14:15], v[8:9] op_sel:[1,0,0] op_sel_hi:[1,1,1]
	v_fmac_f32_e32 v22, s16, v87
	v_readlane_b32 s12, v156, 60
	v_readlane_b32 s13, v157, 60
	v_readlane_b32 s14, v158, 60
	v_readlane_b32 s15, v159, 60
	v_readlane_b32 s16, v160, 60
	s_waitcnt vmcnt(63)
	v_pk_fma_f32 v[10:11], v[88:89], s[12:13], v[10:11] op_sel_hi:[0,1,1]
	v_pk_fma_f32 v[8:9], v[88:89], s[14:15], v[8:9] op_sel_hi:[0,1,1]
	v_fmac_f32_e32 v22, s16, v88
	v_readlane_b32 s12, v156, 61
	v_readlane_b32 s13, v157, 61
	v_readlane_b32 s14, v158, 61
	v_readlane_b32 s15, v159, 61
	v_readlane_b32 s16, v160, 61
	s_waitcnt vmcnt(63)
	v_pk_fma_f32 v[10:11], v[88:89], s[12:13], v[10:11] op_sel:[1,0,0] op_sel_hi:[1,1,1]
	v_pk_fma_f32 v[8:9], v[88:89], s[14:15], v[8:9] op_sel:[1,0,0] op_sel_hi:[1,1,1]
	v_fmac_f32_e32 v22, s16, v89
	v_readlane_b32 s12, v156, 62
	v_readlane_b32 s13, v157, 62
	v_readlane_b32 s14, v158, 62
	v_readlane_b32 s15, v159, 62
	v_readlane_b32 s16, v160, 62
	s_waitcnt vmcnt(63)
	v_pk_fma_f32 v[10:11], v[90:91], s[12:13], v[10:11] op_sel_hi:[0,1,1]
	v_pk_fma_f32 v[8:9], v[90:91], s[14:15], v[8:9] op_sel_hi:[0,1,1]
	v_fmac_f32_e32 v22, s16, v90
	v_readlane_b32 s12, v156, 63
	v_readlane_b32 s13, v157, 63
	v_readlane_b32 s14, v158, 63
	v_readlane_b32 s15, v159, 63
	v_readlane_b32 s16, v160, 63
	s_waitcnt vmcnt(63)
	v_pk_fma_f32 v[10:11], v[90:91], s[12:13], v[10:11] op_sel:[1,0,0] op_sel_hi:[1,1,1]
	v_pk_fma_f32 v[8:9], v[90:91], s[14:15], v[8:9] op_sel:[1,0,0] op_sel_hi:[1,1,1]
	v_fmac_f32_e32 v22, s16, v91
	v_readlane_b32 s12, v161, 0
	v_readlane_b32 s13, v162, 0
	v_readlane_b32 s14, v163, 0
	v_readlane_b32 s15, v164, 0
	v_readlane_b32 s16, v165, 0
	s_waitcnt vmcnt(63)
	v_pk_fma_f32 v[10:11], v[92:93], s[12:13], v[10:11] op_sel_hi:[0,1,1]
	v_pk_fma_f32 v[8:9], v[92:93], s[14:15], v[8:9] op_sel_hi:[0,1,1]
	v_fmac_f32_e32 v22, s16, v92
	v_readlane_b32 s12, v161, 1
	v_readlane_b32 s13, v162, 1
	v_readlane_b32 s14, v163, 1
	v_readlane_b32 s15, v164, 1
	v_readlane_b32 s16, v165, 1
	s_waitcnt vmcnt(62)
	v_pk_fma_f32 v[10:11], v[92:93], s[12:13], v[10:11] op_sel:[1,0,0] op_sel_hi:[1,1,1]
	v_pk_fma_f32 v[8:9], v[92:93], s[14:15], v[8:9] op_sel:[1,0,0] op_sel_hi:[1,1,1]
	v_fmac_f32_e32 v22, s16, v93
	v_readlane_b32 s12, v161, 2
	v_readlane_b32 s13, v162, 2
	v_readlane_b32 s14, v163, 2
	v_readlane_b32 s15, v164, 2
	v_readlane_b32 s16, v165, 2
	s_waitcnt vmcnt(61)
	v_pk_fma_f32 v[10:11], v[94:95], s[12:13], v[10:11] op_sel_hi:[0,1,1]
	v_pk_fma_f32 v[8:9], v[94:95], s[14:15], v[8:9] op_sel_hi:[0,1,1]
	v_fmac_f32_e32 v22, s16, v94
	v_readlane_b32 s12, v161, 3
	v_readlane_b32 s13, v162, 3
	v_readlane_b32 s14, v163, 3
	v_readlane_b32 s15, v164, 3
	v_readlane_b32 s16, v165, 3
	s_waitcnt vmcnt(60)
	v_pk_fma_f32 v[10:11], v[94:95], s[12:13], v[10:11] op_sel:[1,0,0] op_sel_hi:[1,1,1]
	v_pk_fma_f32 v[8:9], v[94:95], s[14:15], v[8:9] op_sel:[1,0,0] op_sel_hi:[1,1,1]
	v_fmac_f32_e32 v22, s16, v95
	v_readlane_b32 s12, v161, 4
	v_readlane_b32 s13, v162, 4
	v_readlane_b32 s14, v163, 4
	v_readlane_b32 s15, v164, 4
	v_readlane_b32 s16, v165, 4
	s_waitcnt vmcnt(59)
	v_pk_fma_f32 v[10:11], v[96:97], s[12:13], v[10:11] op_sel_hi:[0,1,1]
	v_pk_fma_f32 v[8:9], v[96:97], s[14:15], v[8:9] op_sel_hi:[0,1,1]
	v_fmac_f32_e32 v22, s16, v96
	v_readlane_b32 s12, v161, 5
	v_readlane_b32 s13, v162, 5
	v_readlane_b32 s14, v163, 5
	v_readlane_b32 s15, v164, 5
	v_readlane_b32 s16, v165, 5
	s_waitcnt vmcnt(58)
	v_pk_fma_f32 v[10:11], v[96:97], s[12:13], v[10:11] op_sel:[1,0,0] op_sel_hi:[1,1,1]
	v_pk_fma_f32 v[8:9], v[96:97], s[14:15], v[8:9] op_sel:[1,0,0] op_sel_hi:[1,1,1]
	v_fmac_f32_e32 v22, s16, v97
	v_readlane_b32 s12, v161, 6
	v_readlane_b32 s13, v162, 6
	v_readlane_b32 s14, v163, 6
	v_readlane_b32 s15, v164, 6
	v_readlane_b32 s16, v165, 6
	s_waitcnt vmcnt(57)
	v_pk_fma_f32 v[10:11], v[98:99], s[12:13], v[10:11] op_sel_hi:[0,1,1]
	v_pk_fma_f32 v[8:9], v[98:99], s[14:15], v[8:9] op_sel_hi:[0,1,1]
	v_fmac_f32_e32 v22, s16, v98
	v_readlane_b32 s12, v161, 7
	v_readlane_b32 s13, v162, 7
	v_readlane_b32 s14, v163, 7
	v_readlane_b32 s15, v164, 7
	v_readlane_b32 s16, v165, 7
	s_waitcnt vmcnt(56)
	v_pk_fma_f32 v[10:11], v[98:99], s[12:13], v[10:11] op_sel:[1,0,0] op_sel_hi:[1,1,1]
	v_pk_fma_f32 v[8:9], v[98:99], s[14:15], v[8:9] op_sel:[1,0,0] op_sel_hi:[1,1,1]
	v_fmac_f32_e32 v22, s16, v99
	v_readlane_b32 s12, v161, 8
	v_readlane_b32 s13, v162, 8
	v_readlane_b32 s14, v163, 8
	v_readlane_b32 s15, v164, 8
	v_readlane_b32 s16, v165, 8
	s_waitcnt vmcnt(55)
	v_pk_fma_f32 v[10:11], v[100:101], s[12:13], v[10:11] op_sel_hi:[0,1,1]
	v_pk_fma_f32 v[8:9], v[100:101], s[14:15], v[8:9] op_sel_hi:[0,1,1]
	v_fmac_f32_e32 v22, s16, v100
	v_readlane_b32 s12, v161, 9
	v_readlane_b32 s13, v162, 9
	v_readlane_b32 s14, v163, 9
	v_readlane_b32 s15, v164, 9
	v_readlane_b32 s16, v165, 9
	s_waitcnt vmcnt(54)
	v_pk_fma_f32 v[10:11], v[100:101], s[12:13], v[10:11] op_sel:[1,0,0] op_sel_hi:[1,1,1]
	v_pk_fma_f32 v[8:9], v[100:101], s[14:15], v[8:9] op_sel:[1,0,0] op_sel_hi:[1,1,1]
	v_fmac_f32_e32 v22, s16, v101
	v_readlane_b32 s12, v161, 10
	v_readlane_b32 s13, v162, 10
	v_readlane_b32 s14, v163, 10
	v_readlane_b32 s15, v164, 10
	v_readlane_b32 s16, v165, 10
	s_waitcnt vmcnt(53)
	v_pk_fma_f32 v[10:11], v[102:103], s[12:13], v[10:11] op_sel_hi:[0,1,1]
	v_pk_fma_f32 v[8:9], v[102:103], s[14:15], v[8:9] op_sel_hi:[0,1,1]
	v_fmac_f32_e32 v22, s16, v102
	v_readlane_b32 s12, v161, 11
	v_readlane_b32 s13, v162, 11
	v_readlane_b32 s14, v163, 11
	v_readlane_b32 s15, v164, 11
	v_readlane_b32 s16, v165, 11
	s_waitcnt vmcnt(52)
	v_pk_fma_f32 v[10:11], v[102:103], s[12:13], v[10:11] op_sel:[1,0,0] op_sel_hi:[1,1,1]
	v_pk_fma_f32 v[8:9], v[102:103], s[14:15], v[8:9] op_sel:[1,0,0] op_sel_hi:[1,1,1]
	v_fmac_f32_e32 v22, s16, v103
	v_readlane_b32 s12, v161, 12
	v_readlane_b32 s13, v162, 12
	v_readlane_b32 s14, v163, 12
	v_readlane_b32 s15, v164, 12
	v_readlane_b32 s16, v165, 12
	s_waitcnt vmcnt(51)
	v_pk_fma_f32 v[10:11], v[104:105], s[12:13], v[10:11] op_sel_hi:[0,1,1]
	v_pk_fma_f32 v[8:9], v[104:105], s[14:15], v[8:9] op_sel_hi:[0,1,1]
	v_fmac_f32_e32 v22, s16, v104
	v_readlane_b32 s12, v161, 13
	v_readlane_b32 s13, v162, 13
	v_readlane_b32 s14, v163, 13
	v_readlane_b32 s15, v164, 13
	v_readlane_b32 s16, v165, 13
	s_waitcnt vmcnt(50)
	v_pk_fma_f32 v[10:11], v[104:105], s[12:13], v[10:11] op_sel:[1,0,0] op_sel_hi:[1,1,1]
	v_pk_fma_f32 v[8:9], v[104:105], s[14:15], v[8:9] op_sel:[1,0,0] op_sel_hi:[1,1,1]
	v_fmac_f32_e32 v22, s16, v105
	v_readlane_b32 s12, v161, 14
	v_readlane_b32 s13, v162, 14
	v_readlane_b32 s14, v163, 14
	v_readlane_b32 s15, v164, 14
	v_readlane_b32 s16, v165, 14
	s_waitcnt vmcnt(49)
	v_pk_fma_f32 v[10:11], v[106:107], s[12:13], v[10:11] op_sel_hi:[0,1,1]
	v_pk_fma_f32 v[8:9], v[106:107], s[14:15], v[8:9] op_sel_hi:[0,1,1]
	v_fmac_f32_e32 v22, s16, v106
	v_readlane_b32 s12, v161, 15
	v_readlane_b32 s13, v162, 15
	v_readlane_b32 s14, v163, 15
	v_readlane_b32 s15, v164, 15
	v_readlane_b32 s16, v165, 15
	s_waitcnt vmcnt(48)
	v_pk_fma_f32 v[10:11], v[106:107], s[12:13], v[10:11] op_sel:[1,0,0] op_sel_hi:[1,1,1]
	v_pk_fma_f32 v[8:9], v[106:107], s[14:15], v[8:9] op_sel:[1,0,0] op_sel_hi:[1,1,1]
	v_fmac_f32_e32 v22, s16, v107
	v_readlane_b32 s12, v161, 16
	v_readlane_b32 s13, v162, 16
	v_readlane_b32 s14, v163, 16
	v_readlane_b32 s15, v164, 16
	v_readlane_b32 s16, v165, 16
	s_waitcnt vmcnt(47)
	v_pk_fma_f32 v[10:11], v[108:109], s[12:13], v[10:11] op_sel_hi:[0,1,1]
	v_pk_fma_f32 v[8:9], v[108:109], s[14:15], v[8:9] op_sel_hi:[0,1,1]
	v_fmac_f32_e32 v22, s16, v108
	v_readlane_b32 s12, v161, 17
	v_readlane_b32 s13, v162, 17
	v_readlane_b32 s14, v163, 17
	v_readlane_b32 s15, v164, 17
	v_readlane_b32 s16, v165, 17
	s_waitcnt vmcnt(46)
	v_pk_fma_f32 v[10:11], v[108:109], s[12:13], v[10:11] op_sel:[1,0,0] op_sel_hi:[1,1,1]
	v_pk_fma_f32 v[8:9], v[108:109], s[14:15], v[8:9] op_sel:[1,0,0] op_sel_hi:[1,1,1]
	v_fmac_f32_e32 v22, s16, v109
	v_readlane_b32 s12, v161, 18
	v_readlane_b32 s13, v162, 18
	v_readlane_b32 s14, v163, 18
	v_readlane_b32 s15, v164, 18
	v_readlane_b32 s16, v165, 18
	s_waitcnt vmcnt(45)
	v_pk_fma_f32 v[10:11], v[110:111], s[12:13], v[10:11] op_sel_hi:[0,1,1]
	v_pk_fma_f32 v[8:9], v[110:111], s[14:15], v[8:9] op_sel_hi:[0,1,1]
	v_fmac_f32_e32 v22, s16, v110
	v_readlane_b32 s12, v161, 19
	v_readlane_b32 s13, v162, 19
	v_readlane_b32 s14, v163, 19
	v_readlane_b32 s15, v164, 19
	v_readlane_b32 s16, v165, 19
	s_waitcnt vmcnt(44)
	v_pk_fma_f32 v[10:11], v[110:111], s[12:13], v[10:11] op_sel:[1,0,0] op_sel_hi:[1,1,1]
	v_pk_fma_f32 v[8:9], v[110:111], s[14:15], v[8:9] op_sel:[1,0,0] op_sel_hi:[1,1,1]
	v_fmac_f32_e32 v22, s16, v111
	v_readlane_b32 s12, v161, 20
	v_readlane_b32 s13, v162, 20
	v_readlane_b32 s14, v163, 20
	v_readlane_b32 s15, v164, 20
	v_readlane_b32 s16, v165, 20
	s_waitcnt vmcnt(43)
	v_pk_fma_f32 v[10:11], v[112:113], s[12:13], v[10:11] op_sel_hi:[0,1,1]
	v_pk_fma_f32 v[8:9], v[112:113], s[14:15], v[8:9] op_sel_hi:[0,1,1]
	v_fmac_f32_e32 v22, s16, v112
	v_readlane_b32 s12, v161, 21
	v_readlane_b32 s13, v162, 21
	v_readlane_b32 s14, v163, 21
	v_readlane_b32 s15, v164, 21
	v_readlane_b32 s16, v165, 21
	s_waitcnt vmcnt(42)
	v_pk_fma_f32 v[10:11], v[112:113], s[12:13], v[10:11] op_sel:[1,0,0] op_sel_hi:[1,1,1]
	v_pk_fma_f32 v[8:9], v[112:113], s[14:15], v[8:9] op_sel:[1,0,0] op_sel_hi:[1,1,1]
	v_fmac_f32_e32 v22, s16, v113
	v_readlane_b32 s12, v161, 22
	v_readlane_b32 s13, v162, 22
	v_readlane_b32 s14, v163, 22
	v_readlane_b32 s15, v164, 22
	v_readlane_b32 s16, v165, 22
	s_waitcnt vmcnt(41)
	v_pk_fma_f32 v[10:11], v[114:115], s[12:13], v[10:11] op_sel_hi:[0,1,1]
	v_pk_fma_f32 v[8:9], v[114:115], s[14:15], v[8:9] op_sel_hi:[0,1,1]
	v_fmac_f32_e32 v22, s16, v114
	v_readlane_b32 s12, v161, 23
	v_readlane_b32 s13, v162, 23
	v_readlane_b32 s14, v163, 23
	v_readlane_b32 s15, v164, 23
	v_readlane_b32 s16, v165, 23
	s_waitcnt vmcnt(40)
	v_pk_fma_f32 v[10:11], v[114:115], s[12:13], v[10:11] op_sel:[1,0,0] op_sel_hi:[1,1,1]
	v_pk_fma_f32 v[8:9], v[114:115], s[14:15], v[8:9] op_sel:[1,0,0] op_sel_hi:[1,1,1]
	v_fmac_f32_e32 v22, s16, v115
	v_readlane_b32 s12, v161, 24
	v_readlane_b32 s13, v162, 24
	v_readlane_b32 s14, v163, 24
	v_readlane_b32 s15, v164, 24
	v_readlane_b32 s16, v165, 24
	s_waitcnt vmcnt(39)
	v_pk_fma_f32 v[10:11], v[116:117], s[12:13], v[10:11] op_sel_hi:[0,1,1]
	v_pk_fma_f32 v[8:9], v[116:117], s[14:15], v[8:9] op_sel_hi:[0,1,1]
	v_fmac_f32_e32 v22, s16, v116
	v_readlane_b32 s12, v161, 25
	v_readlane_b32 s13, v162, 25
	v_readlane_b32 s14, v163, 25
	v_readlane_b32 s15, v164, 25
	v_readlane_b32 s16, v165, 25
	s_waitcnt vmcnt(38)
	v_pk_fma_f32 v[10:11], v[116:117], s[12:13], v[10:11] op_sel:[1,0,0] op_sel_hi:[1,1,1]
	v_pk_fma_f32 v[8:9], v[116:117], s[14:15], v[8:9] op_sel:[1,0,0] op_sel_hi:[1,1,1]
	v_fmac_f32_e32 v22, s16, v117
	v_readlane_b32 s12, v161, 26
	v_readlane_b32 s13, v162, 26
	v_readlane_b32 s14, v163, 26
	v_readlane_b32 s15, v164, 26
	v_readlane_b32 s16, v165, 26
	s_waitcnt vmcnt(37)
	v_pk_fma_f32 v[10:11], v[118:119], s[12:13], v[10:11] op_sel_hi:[0,1,1]
	v_pk_fma_f32 v[8:9], v[118:119], s[14:15], v[8:9] op_sel_hi:[0,1,1]
	v_fmac_f32_e32 v22, s16, v118
	v_readlane_b32 s12, v161, 27
	v_readlane_b32 s13, v162, 27
	v_readlane_b32 s14, v163, 27
	v_readlane_b32 s15, v164, 27
	v_readlane_b32 s16, v165, 27
	s_waitcnt vmcnt(36)
	v_pk_fma_f32 v[10:11], v[118:119], s[12:13], v[10:11] op_sel:[1,0,0] op_sel_hi:[1,1,1]
	v_pk_fma_f32 v[8:9], v[118:119], s[14:15], v[8:9] op_sel:[1,0,0] op_sel_hi:[1,1,1]
	v_fmac_f32_e32 v22, s16, v119
	v_readlane_b32 s12, v161, 28
	v_readlane_b32 s13, v162, 28
	v_readlane_b32 s14, v163, 28
	v_readlane_b32 s15, v164, 28
	v_readlane_b32 s16, v165, 28
	s_waitcnt vmcnt(35)
	v_pk_fma_f32 v[10:11], v[120:121], s[12:13], v[10:11] op_sel_hi:[0,1,1]
	v_pk_fma_f32 v[8:9], v[120:121], s[14:15], v[8:9] op_sel_hi:[0,1,1]
	v_fmac_f32_e32 v22, s16, v120
	v_readlane_b32 s12, v161, 29
	v_readlane_b32 s13, v162, 29
	v_readlane_b32 s14, v163, 29
	v_readlane_b32 s15, v164, 29
	v_readlane_b32 s16, v165, 29
	s_waitcnt vmcnt(34)
	v_pk_fma_f32 v[10:11], v[120:121], s[12:13], v[10:11] op_sel:[1,0,0] op_sel_hi:[1,1,1]
	v_pk_fma_f32 v[8:9], v[120:121], s[14:15], v[8:9] op_sel:[1,0,0] op_sel_hi:[1,1,1]
	v_fmac_f32_e32 v22, s16, v121
	v_readlane_b32 s12, v161, 30
	v_readlane_b32 s13, v162, 30
	v_readlane_b32 s14, v163, 30
	v_readlane_b32 s15, v164, 30
	v_readlane_b32 s16, v165, 30
	s_waitcnt vmcnt(33)
	v_pk_fma_f32 v[10:11], v[122:123], s[12:13], v[10:11] op_sel_hi:[0,1,1]
	v_pk_fma_f32 v[8:9], v[122:123], s[14:15], v[8:9] op_sel_hi:[0,1,1]
	v_fmac_f32_e32 v22, s16, v122
	v_readlane_b32 s12, v161, 31
	v_readlane_b32 s13, v162, 31
	v_readlane_b32 s14, v163, 31
	v_readlane_b32 s15, v164, 31
	v_readlane_b32 s16, v165, 31
	s_waitcnt vmcnt(32)
	v_pk_fma_f32 v[10:11], v[122:123], s[12:13], v[10:11] op_sel:[1,0,0] op_sel_hi:[1,1,1]
	v_pk_fma_f32 v[8:9], v[122:123], s[14:15], v[8:9] op_sel:[1,0,0] op_sel_hi:[1,1,1]
	v_fmac_f32_e32 v22, s16, v123
	v_readlane_b32 s12, v161, 32
	v_readlane_b32 s13, v162, 32
	v_readlane_b32 s14, v163, 32
	v_readlane_b32 s15, v164, 32
	v_readlane_b32 s16, v165, 32
	s_waitcnt vmcnt(31)
	v_pk_fma_f32 v[10:11], v[124:125], s[12:13], v[10:11] op_sel_hi:[0,1,1]
	v_pk_fma_f32 v[8:9], v[124:125], s[14:15], v[8:9] op_sel_hi:[0,1,1]
	v_fmac_f32_e32 v22, s16, v124
	v_readlane_b32 s12, v161, 33
	v_readlane_b32 s13, v162, 33
	v_readlane_b32 s14, v163, 33
	v_readlane_b32 s15, v164, 33
	v_readlane_b32 s16, v165, 33
	s_waitcnt vmcnt(30)
	v_pk_fma_f32 v[10:11], v[124:125], s[12:13], v[10:11] op_sel:[1,0,0] op_sel_hi:[1,1,1]
	v_pk_fma_f32 v[8:9], v[124:125], s[14:15], v[8:9] op_sel:[1,0,0] op_sel_hi:[1,1,1]
	v_fmac_f32_e32 v22, s16, v125
	v_readlane_b32 s12, v161, 34
	v_readlane_b32 s13, v162, 34
	v_readlane_b32 s14, v163, 34
	v_readlane_b32 s15, v164, 34
	v_readlane_b32 s16, v165, 34
	s_waitcnt vmcnt(29)
	v_pk_fma_f32 v[10:11], v[126:127], s[12:13], v[10:11] op_sel_hi:[0,1,1]
	v_pk_fma_f32 v[8:9], v[126:127], s[14:15], v[8:9] op_sel_hi:[0,1,1]
	v_fmac_f32_e32 v22, s16, v126
	v_readlane_b32 s12, v161, 35
	v_readlane_b32 s13, v162, 35
	v_readlane_b32 s14, v163, 35
	v_readlane_b32 s15, v164, 35
	v_readlane_b32 s16, v165, 35
	s_waitcnt vmcnt(28)
	v_pk_fma_f32 v[10:11], v[126:127], s[12:13], v[10:11] op_sel:[1,0,0] op_sel_hi:[1,1,1]
	v_pk_fma_f32 v[8:9], v[126:127], s[14:15], v[8:9] op_sel:[1,0,0] op_sel_hi:[1,1,1]
	v_fmac_f32_e32 v22, s16, v127
	v_readlane_b32 s12, v161, 36
	v_readlane_b32 s13, v162, 36
	v_readlane_b32 s14, v163, 36
	v_readlane_b32 s15, v164, 36
	v_readlane_b32 s16, v165, 36
	s_waitcnt vmcnt(27)
	v_pk_fma_f32 v[10:11], v[128:129], s[12:13], v[10:11] op_sel_hi:[0,1,1]
	v_pk_fma_f32 v[8:9], v[128:129], s[14:15], v[8:9] op_sel_hi:[0,1,1]
	v_fmac_f32_e32 v22, s16, v128
	v_readlane_b32 s12, v161, 37
	v_readlane_b32 s13, v162, 37
	v_readlane_b32 s14, v163, 37
	v_readlane_b32 s15, v164, 37
	v_readlane_b32 s16, v165, 37
	s_waitcnt vmcnt(26)
	v_pk_fma_f32 v[10:11], v[128:129], s[12:13], v[10:11] op_sel:[1,0,0] op_sel_hi:[1,1,1]
	v_pk_fma_f32 v[8:9], v[128:129], s[14:15], v[8:9] op_sel:[1,0,0] op_sel_hi:[1,1,1]
	v_fmac_f32_e32 v22, s16, v129
	v_readlane_b32 s12, v161, 38
	v_readlane_b32 s13, v162, 38
	v_readlane_b32 s14, v163, 38
	v_readlane_b32 s15, v164, 38
	v_readlane_b32 s16, v165, 38
	s_waitcnt vmcnt(25)
	v_pk_fma_f32 v[10:11], v[130:131], s[12:13], v[10:11] op_sel_hi:[0,1,1]
	v_pk_fma_f32 v[8:9], v[130:131], s[14:15], v[8:9] op_sel_hi:[0,1,1]
	v_fmac_f32_e32 v22, s16, v130
	v_readlane_b32 s12, v161, 39
	v_readlane_b32 s13, v162, 39
	v_readlane_b32 s14, v163, 39
	v_readlane_b32 s15, v164, 39
	v_readlane_b32 s16, v165, 39
	s_waitcnt vmcnt(24)
	v_pk_fma_f32 v[10:11], v[130:131], s[12:13], v[10:11] op_sel:[1,0,0] op_sel_hi:[1,1,1]
	v_pk_fma_f32 v[8:9], v[130:131], s[14:15], v[8:9] op_sel:[1,0,0] op_sel_hi:[1,1,1]
	v_fmac_f32_e32 v22, s16, v131
	v_readlane_b32 s12, v161, 40
	v_readlane_b32 s13, v162, 40
	v_readlane_b32 s14, v163, 40
	v_readlane_b32 s15, v164, 40
	v_readlane_b32 s16, v165, 40
	s_waitcnt vmcnt(23)
	v_pk_fma_f32 v[10:11], v[132:133], s[12:13], v[10:11] op_sel_hi:[0,1,1]
	v_pk_fma_f32 v[8:9], v[132:133], s[14:15], v[8:9] op_sel_hi:[0,1,1]
	v_fmac_f32_e32 v22, s16, v132
	v_readlane_b32 s12, v161, 41
	v_readlane_b32 s13, v162, 41
	v_readlane_b32 s14, v163, 41
	v_readlane_b32 s15, v164, 41
	v_readlane_b32 s16, v165, 41
	s_waitcnt vmcnt(22)
	v_pk_fma_f32 v[10:11], v[132:133], s[12:13], v[10:11] op_sel:[1,0,0] op_sel_hi:[1,1,1]
	v_pk_fma_f32 v[8:9], v[132:133], s[14:15], v[8:9] op_sel:[1,0,0] op_sel_hi:[1,1,1]
	v_fmac_f32_e32 v22, s16, v133
	v_readlane_b32 s12, v161, 42
	v_readlane_b32 s13, v162, 42
	v_readlane_b32 s14, v163, 42
	v_readlane_b32 s15, v164, 42
	v_readlane_b32 s16, v165, 42
	s_waitcnt vmcnt(21)
	v_pk_fma_f32 v[10:11], v[134:135], s[12:13], v[10:11] op_sel_hi:[0,1,1]
	v_pk_fma_f32 v[8:9], v[134:135], s[14:15], v[8:9] op_sel_hi:[0,1,1]
	v_fmac_f32_e32 v22, s16, v134
	v_readlane_b32 s12, v161, 43
	v_readlane_b32 s13, v162, 43
	v_readlane_b32 s14, v163, 43
	v_readlane_b32 s15, v164, 43
	v_readlane_b32 s16, v165, 43
	s_waitcnt vmcnt(20)
	v_pk_fma_f32 v[10:11], v[134:135], s[12:13], v[10:11] op_sel:[1,0,0] op_sel_hi:[1,1,1]
	v_pk_fma_f32 v[8:9], v[134:135], s[14:15], v[8:9] op_sel:[1,0,0] op_sel_hi:[1,1,1]
	v_fmac_f32_e32 v22, s16, v135
	v_readlane_b32 s12, v161, 44
	v_readlane_b32 s13, v162, 44
	v_readlane_b32 s14, v163, 44
	v_readlane_b32 s15, v164, 44
	v_readlane_b32 s16, v165, 44
	s_waitcnt vmcnt(19)
	v_pk_fma_f32 v[10:11], v[136:137], s[12:13], v[10:11] op_sel_hi:[0,1,1]
	v_pk_fma_f32 v[8:9], v[136:137], s[14:15], v[8:9] op_sel_hi:[0,1,1]
	v_fmac_f32_e32 v22, s16, v136
	v_readlane_b32 s12, v161, 45
	v_readlane_b32 s13, v162, 45
	v_readlane_b32 s14, v163, 45
	v_readlane_b32 s15, v164, 45
	v_readlane_b32 s16, v165, 45
	s_waitcnt vmcnt(18)
	v_pk_fma_f32 v[10:11], v[136:137], s[12:13], v[10:11] op_sel:[1,0,0] op_sel_hi:[1,1,1]
	v_pk_fma_f32 v[8:9], v[136:137], s[14:15], v[8:9] op_sel:[1,0,0] op_sel_hi:[1,1,1]
	v_fmac_f32_e32 v22, s16, v137
	v_readlane_b32 s12, v161, 46
	v_readlane_b32 s13, v162, 46
	v_readlane_b32 s14, v163, 46
	v_readlane_b32 s15, v164, 46
	v_readlane_b32 s16, v165, 46
	s_waitcnt vmcnt(17)
	v_pk_fma_f32 v[10:11], v[138:139], s[12:13], v[10:11] op_sel_hi:[0,1,1]
	v_pk_fma_f32 v[8:9], v[138:139], s[14:15], v[8:9] op_sel_hi:[0,1,1]
	v_fmac_f32_e32 v22, s16, v138
	v_readlane_b32 s12, v161, 47
	v_readlane_b32 s13, v162, 47
	v_readlane_b32 s14, v163, 47
	v_readlane_b32 s15, v164, 47
	v_readlane_b32 s16, v165, 47
	s_waitcnt vmcnt(16)
	v_pk_fma_f32 v[10:11], v[138:139], s[12:13], v[10:11] op_sel:[1,0,0] op_sel_hi:[1,1,1]
	v_pk_fma_f32 v[8:9], v[138:139], s[14:15], v[8:9] op_sel:[1,0,0] op_sel_hi:[1,1,1]
	v_fmac_f32_e32 v22, s16, v139
	v_readlane_b32 s12, v161, 48
	v_readlane_b32 s13, v162, 48
	v_readlane_b32 s14, v163, 48
	v_readlane_b32 s15, v164, 48
	v_readlane_b32 s16, v165, 48
	s_waitcnt vmcnt(15)
	v_pk_fma_f32 v[10:11], v[140:141], s[12:13], v[10:11] op_sel_hi:[0,1,1]
	v_pk_fma_f32 v[8:9], v[140:141], s[14:15], v[8:9] op_sel_hi:[0,1,1]
	v_fmac_f32_e32 v22, s16, v140
	v_readlane_b32 s12, v161, 49
	v_readlane_b32 s13, v162, 49
	v_readlane_b32 s14, v163, 49
	v_readlane_b32 s15, v164, 49
	v_readlane_b32 s16, v165, 49
	s_waitcnt vmcnt(14)
	v_pk_fma_f32 v[10:11], v[140:141], s[12:13], v[10:11] op_sel:[1,0,0] op_sel_hi:[1,1,1]
	v_pk_fma_f32 v[8:9], v[140:141], s[14:15], v[8:9] op_sel:[1,0,0] op_sel_hi:[1,1,1]
	v_fmac_f32_e32 v22, s16, v141
	v_readlane_b32 s12, v161, 50
	v_readlane_b32 s13, v162, 50
	v_readlane_b32 s14, v163, 50
	v_readlane_b32 s15, v164, 50
	v_readlane_b32 s16, v165, 50
	s_waitcnt vmcnt(13)
	v_pk_fma_f32 v[10:11], v[142:143], s[12:13], v[10:11] op_sel_hi:[0,1,1]
	v_pk_fma_f32 v[8:9], v[142:143], s[14:15], v[8:9] op_sel_hi:[0,1,1]
	v_fmac_f32_e32 v22, s16, v142
	v_readlane_b32 s12, v161, 51
	v_readlane_b32 s13, v162, 51
	v_readlane_b32 s14, v163, 51
	v_readlane_b32 s15, v164, 51
	v_readlane_b32 s16, v165, 51
	s_waitcnt vmcnt(12)
	v_pk_fma_f32 v[10:11], v[142:143], s[12:13], v[10:11] op_sel:[1,0,0] op_sel_hi:[1,1,1]
	v_pk_fma_f32 v[8:9], v[142:143], s[14:15], v[8:9] op_sel:[1,0,0] op_sel_hi:[1,1,1]
	v_fmac_f32_e32 v22, s16, v143
	v_readlane_b32 s12, v161, 52
	v_readlane_b32 s13, v162, 52
	v_readlane_b32 s14, v163, 52
	v_readlane_b32 s15, v164, 52
	v_readlane_b32 s16, v165, 52
	s_waitcnt vmcnt(11)
	v_pk_fma_f32 v[10:11], v[144:145], s[12:13], v[10:11] op_sel_hi:[0,1,1]
	v_pk_fma_f32 v[8:9], v[144:145], s[14:15], v[8:9] op_sel_hi:[0,1,1]
	v_fmac_f32_e32 v22, s16, v144
	v_readlane_b32 s12, v161, 53
	v_readlane_b32 s13, v162, 53
	v_readlane_b32 s14, v163, 53
	v_readlane_b32 s15, v164, 53
	v_readlane_b32 s16, v165, 53
	s_waitcnt vmcnt(10)
	v_pk_fma_f32 v[10:11], v[144:145], s[12:13], v[10:11] op_sel:[1,0,0] op_sel_hi:[1,1,1]
	v_pk_fma_f32 v[8:9], v[144:145], s[14:15], v[8:9] op_sel:[1,0,0] op_sel_hi:[1,1,1]
	v_fmac_f32_e32 v22, s16, v145
	v_readlane_b32 s12, v161, 54
	v_readlane_b32 s13, v162, 54
	v_readlane_b32 s14, v163, 54
	v_readlane_b32 s15, v164, 54
	v_readlane_b32 s16, v165, 54
	s_waitcnt vmcnt(9)
	v_pk_fma_f32 v[10:11], v[146:147], s[12:13], v[10:11] op_sel_hi:[0,1,1]
	v_pk_fma_f32 v[8:9], v[146:147], s[14:15], v[8:9] op_sel_hi:[0,1,1]
	v_fmac_f32_e32 v22, s16, v146
	v_readlane_b32 s12, v161, 55
	v_readlane_b32 s13, v162, 55
	v_readlane_b32 s14, v163, 55
	v_readlane_b32 s15, v164, 55
	v_readlane_b32 s16, v165, 55
	s_waitcnt vmcnt(8)
	v_pk_fma_f32 v[10:11], v[146:147], s[12:13], v[10:11] op_sel:[1,0,0] op_sel_hi:[1,1,1]
	v_pk_fma_f32 v[8:9], v[146:147], s[14:15], v[8:9] op_sel:[1,0,0] op_sel_hi:[1,1,1]
	v_fmac_f32_e32 v22, s16, v147
	v_readlane_b32 s12, v161, 56
	v_readlane_b32 s13, v162, 56
	v_readlane_b32 s14, v163, 56
	v_readlane_b32 s15, v164, 56
	v_readlane_b32 s16, v165, 56
	s_waitcnt vmcnt(7)
	v_pk_fma_f32 v[10:11], v[148:149], s[12:13], v[10:11] op_sel_hi:[0,1,1]
	v_pk_fma_f32 v[8:9], v[148:149], s[14:15], v[8:9] op_sel_hi:[0,1,1]
	v_fmac_f32_e32 v22, s16, v148
	v_readlane_b32 s12, v161, 57
	v_readlane_b32 s13, v162, 57
	v_readlane_b32 s14, v163, 57
	v_readlane_b32 s15, v164, 57
	v_readlane_b32 s16, v165, 57
	s_waitcnt vmcnt(6)
	v_pk_fma_f32 v[10:11], v[148:149], s[12:13], v[10:11] op_sel:[1,0,0] op_sel_hi:[1,1,1]
	v_pk_fma_f32 v[8:9], v[148:149], s[14:15], v[8:9] op_sel:[1,0,0] op_sel_hi:[1,1,1]
	v_fmac_f32_e32 v22, s16, v149
	v_readlane_b32 s12, v161, 58
	v_readlane_b32 s13, v162, 58
	v_readlane_b32 s14, v163, 58
	v_readlane_b32 s15, v164, 58
	v_readlane_b32 s16, v165, 58
	s_waitcnt vmcnt(5)
	v_pk_fma_f32 v[10:11], v[150:151], s[12:13], v[10:11] op_sel_hi:[0,1,1]
	v_pk_fma_f32 v[8:9], v[150:151], s[14:15], v[8:9] op_sel_hi:[0,1,1]
	v_fmac_f32_e32 v22, s16, v150
	v_readlane_b32 s12, v161, 59
	v_readlane_b32 s13, v162, 59
	v_readlane_b32 s14, v163, 59
	v_readlane_b32 s15, v164, 59
	v_readlane_b32 s16, v165, 59
	s_waitcnt vmcnt(4)
	v_pk_fma_f32 v[10:11], v[150:151], s[12:13], v[10:11] op_sel:[1,0,0] op_sel_hi:[1,1,1]
	v_pk_fma_f32 v[8:9], v[150:151], s[14:15], v[8:9] op_sel:[1,0,0] op_sel_hi:[1,1,1]
	v_fmac_f32_e32 v22, s16, v151
	v_readlane_b32 s12, v161, 60
	v_readlane_b32 s13, v162, 60
	v_readlane_b32 s14, v163, 60
	v_readlane_b32 s15, v164, 60
	v_readlane_b32 s16, v165, 60
	s_waitcnt vmcnt(3)
	v_pk_fma_f32 v[10:11], v[152:153], s[12:13], v[10:11] op_sel_hi:[0,1,1]
	v_pk_fma_f32 v[8:9], v[152:153], s[14:15], v[8:9] op_sel_hi:[0,1,1]
	v_fmac_f32_e32 v22, s16, v152
	v_readlane_b32 s12, v161, 61
	v_readlane_b32 s13, v162, 61
	v_readlane_b32 s14, v163, 61
	v_readlane_b32 s15, v164, 61
	v_readlane_b32 s16, v165, 61
	s_waitcnt vmcnt(2)
	v_pk_fma_f32 v[10:11], v[152:153], s[12:13], v[10:11] op_sel:[1,0,0] op_sel_hi:[1,1,1]
	v_pk_fma_f32 v[8:9], v[152:153], s[14:15], v[8:9] op_sel:[1,0,0] op_sel_hi:[1,1,1]
	v_fmac_f32_e32 v22, s16, v153
	v_readlane_b32 s12, v161, 62
	v_readlane_b32 s13, v162, 62
	v_readlane_b32 s14, v163, 62
	v_readlane_b32 s15, v164, 62
	v_readlane_b32 s16, v165, 62
	s_waitcnt vmcnt(1)
	v_pk_fma_f32 v[10:11], v[154:155], s[12:13], v[10:11] op_sel_hi:[0,1,1]
	v_pk_fma_f32 v[8:9], v[154:155], s[14:15], v[8:9] op_sel_hi:[0,1,1]
	v_fmac_f32_e32 v22, s16, v154
	v_readlane_b32 s12, v161, 63
	v_readlane_b32 s13, v162, 63
	v_readlane_b32 s14, v163, 63
	v_readlane_b32 s15, v164, 63
	v_readlane_b32 s16, v165, 63
	s_waitcnt vmcnt(0)
	v_pk_fma_f32 v[10:11], v[154:155], s[12:13], v[10:11] op_sel:[1,0,0] op_sel_hi:[1,1,1]
	v_pk_fma_f32 v[8:9], v[154:155], s[14:15], v[8:9] op_sel:[1,0,0] op_sel_hi:[1,1,1]
	v_fmac_f32_e32 v22, s16, v155
	s_movk_i32 s12, 0x6000
	s_mov_b32 s13, 0x9000
	s_mov_b32 s14, 0xc000
	s_mov_b32 s15, 0xf000
	s_mov_b32 s16, 0x12000
	v_lshlrev_b32_e32 v0, 3, v17
	v_and_b32_e32 v6, 0xffffffc0, v0
	v_ashrrev_i32_e32 v7, 31, v6
	v_lshl_add_u64 v[6:7], v[6:7], 2, v[2:3]
	v_add_co_u32_e32 v12, vcc, 0x3000, v6
	global_store_dword v[6:7], v10, off
	s_nop 0
	v_addc_co_u32_e32 v13, vcc, 0, v7, vcc
	v_add_co_u32_e32 v10, vcc, 0x6000, v6
	global_store_dword v[12:13], v11, off
	s_nop 0
	v_addc_co_u32_e32 v11, vcc, 0, v7, vcc
	global_store_dword v[10:11], v8, off
	v_add_co_u32_e32 v10, vcc, 0x9000, v6
	v_add_u32_e32 v17, s33, v17
	s_nop 0
	v_addc_co_u32_e32 v11, vcc, 0, v7, vcc
	v_add_co_u32_e32 v6, vcc, 0xc000, v6
	v_add_u32_e32 v19, s3, v19
	s_nop 0
	v_addc_co_u32_e32 v7, vcc, 0, v7, vcc
	v_cmp_lt_i32_e32 vcc, s69, v17
	s_or_b64 s[4:5], vcc, s[4:5]
	global_store_dword v[10:11], v9, off
	global_store_dword v[6:7], v22, off
	s_andn2_b64 exec, exec, s[4:5]
	s_cbranch_execnz .LBB0_19
